# attention unit tail: 4 gate_a loads hoisted above the barrier; dual-GEMM epilogue: 14 gate loads hoisted with counted waits
# speedup vs baseline: 1.0164x; 1.0005x over previous
; __device__ __forceinline__ unsigned cvt_pk_bf16(float lo, float hi) { f32x2 v = {lo, hi}; bf16x2_t b = __builtin_convertvector(v, bf16x2_t); return __builtin_bit_cast(unsigned, b); }
; __device__ __forceinline__ float bf_lo(unsigned w) { return __uint_as_float(w << 16); }
; __device__ __forceinline__ float bf_hi(unsigned w) { return __uint_as_float(w & 0xffff0000u); }
; __device__ __forceinline__ float sigmoidf_fast(float x) { return __builtin_amdgcn_rcpf(1.0f + __builtin_amdgcn_exp2f(-1.4426950408889634f * x)); }
; #define LAS __attribute__((address_space(3)))
; __device__ __forceinline__ void attn_unit(LAS unsigned char* lds, bf16_t* Zg, const unsigned char* KVg, int S, int b, int h, int qb, const float* lq1, const float* lk1, const float* lq2, const float* lk2, const float* subln_g, const float* rel_bias, bool dostore = true) {
;     ...
;     __syncthreads();
; #pragma unroll
;     for (int i = 0; i < 4; ++i) { const int p = (tid >> 4) + 32 * i, c8 = (tid & 15) * 8; bf16_t* zp = Zg + (rowbase + q0 + p) * ZLD + COL_GA + h * 128 + c8;
;         const u32x4 gw = *(const u32x4*)zp; const f32x4 s0 = *(const LAS f32x4*)(exch + p * 128 + c8), s1 = *(const LAS f32x4*)(exch + p * 128 + c8 + 4);
;         const float sv[8] = {s0.x, s0.y, s0.z, s0.w, s1.x, s1.y, s1.z, s1.w}; u32x4 ow;
; #pragma unroll
;         for (int e = 0; e < 4; ++e) { const float g0 = bf_lo(gw[e]), g1 = bf_hi(gw[e]); ow[e] = cvt_pk_bf16(sv[2 * e] * g0 * sigmoidf_fast(g0), sv[2 * e + 1] * g1 * sigmoidf_fast(g1)); }
;         if (dostore) *(u32x4*)zp = ow; }
.LBB0_187:
	s_ashr_i32 s5, s83, 31
	v_ashrrev_i32_e32 v2, 4, v202
	s_add_u32 s4, s82, s83
	s_addc_u32 s5, s17, s5
	v_ashrrev_i32_e32 v3, 31, v2
	v_lshl_add_u64 v[6:7], s[4:5], 0, v[2:3]
	v_mov_b64_e32 v[4:5], s[26:27]
	v_mad_u64_u32 v[8:9], s[6:7], v6, s35, v[4:5]
	v_mov_b32_e32 v0, v9
	v_mad_u64_u32 v[6:7], s[6:7], v7, s35, v[0:1]
	v_and_b32_e32 v11, 0x78, v203
	v_mov_b32_e32 v9, v6
	s_lshl_b32 s18, s16, 8
	v_lshl_add_u64 v[6:7], v[8:9], 0, s[18:19]
	v_lshlrev_b32_e32 v0, 1, v11
	v_lshl_add_u64 v[6:7], v[6:7], 0, v[0:1]
	v_add_co_u32_e32 v20, vcc, s31, v6
	s_waitcnt lgkmcnt(0)
	s_nop 0
	v_addc_co_u32_e32 v21, vcc, 0, v7, vcc
	global_load_dwordx4 v[80:83], v[20:21], off offset:2048
	v_add_co_u32_e32 v96, vcc, 0x90000, v20
	s_nop 1
	v_addc_co_u32_e32 v97, vcc, 0, v21, vcc
	global_load_dwordx4 v[84:87], v[96:97], off offset:2048
	v_add_co_u32_e32 v96, vcc, 0x120000, v20
	s_nop 1
	v_addc_co_u32_e32 v97, vcc, 0, v21, vcc
	global_load_dwordx4 v[88:91], v[96:97], off offset:2048
	v_add_co_u32_e32 v96, vcc, 0x1b0000, v20
	s_nop 1
	v_addc_co_u32_e32 v97, vcc, 0, v21, vcc
	global_load_dwordx4 v[92:95], v[96:97], off offset:2048
	s_barrier
	v_lshl_add_u32 v10, v11, 2, 0
	v_lshl_add_u32 v3, v2, 9, v10
	ds_read_b128 v[12:15], v3
	ds_read_b128 v[16:19], v3 offset:16
	s_add_i32 s94, s94, s3
	s_cmp_lt_i32 s94, s43
	s_waitcnt vmcnt(3)
	v_mov_b64_e32 v[6:7], v[80:81]
	v_mov_b64_e32 v[8:9], v[82:83]
	v_lshlrev_b32_e32 v22, 16, v6
	v_mul_f32_e32 v3, 0xbfb8aa3b, v22
	v_exp_f32_e32 v3, v3
	v_and_b32_e32 v23, 0xffff0000, v6
	s_waitcnt lgkmcnt(1)
	v_pk_mul_f32 v[12:13], v[12:13], v[22:23]
	v_add_f32_e32 v3, 1.0, v3
	v_rcp_f32_e32 v24, v3
	v_mul_f32_e32 v3, 0xbfb8aa3b, v23
	v_exp_f32_e32 v3, v3
	s_nop 0
	v_add_f32_e32 v3, 1.0, v3
	v_rcp_f32_e32 v25, v3
	s_nop 0
	v_pk_mul_f32 v[12:13], v[12:13], v[24:25]
	s_nop 0
	v_cvt_pk_bf16_f32 v6, v12, v13
	v_lshlrev_b32_e32 v12, 16, v7
	v_mul_f32_e32 v3, 0xbfb8aa3b, v12
	v_exp_f32_e32 v3, v3
	v_and_b32_e32 v13, 0xffff0000, v7
	v_pk_mul_f32 v[14:15], v[14:15], v[12:13]
	v_add_f32_e32 v3, 1.0, v3
	v_rcp_f32_e32 v22, v3
	v_mul_f32_e32 v3, 0xbfb8aa3b, v13
	v_exp_f32_e32 v3, v3
	s_nop 0
	v_add_f32_e32 v3, 1.0, v3
	v_rcp_f32_e32 v23, v3
	s_nop 0
	v_pk_mul_f32 v[12:13], v[14:15], v[22:23]
	s_nop 0
	v_cvt_pk_bf16_f32 v7, v12, v13
	v_lshlrev_b32_e32 v12, 16, v8
	v_mul_f32_e32 v3, 0xbfb8aa3b, v12
	v_exp_f32_e32 v3, v3
	v_and_b32_e32 v13, 0xffff0000, v8
	s_waitcnt lgkmcnt(0)
	v_pk_mul_f32 v[16:17], v[16:17], v[12:13]
	v_add_f32_e32 v3, 1.0, v3
	v_rcp_f32_e32 v14, v3
	v_mul_f32_e32 v3, 0xbfb8aa3b, v13
	v_exp_f32_e32 v3, v3
	s_nop 0
	v_add_f32_e32 v3, 1.0, v3
	v_rcp_f32_e32 v15, v3
	s_nop 0
	v_pk_mul_f32 v[12:13], v[16:17], v[14:15]
	s_nop 0
	v_cvt_pk_bf16_f32 v8, v12, v13
	v_lshlrev_b32_e32 v12, 16, v9
	v_mul_f32_e32 v3, 0xbfb8aa3b, v12
	v_exp_f32_e32 v3, v3
	v_and_b32_e32 v13, 0xffff0000, v9
	v_pk_mul_f32 v[16:17], v[18:19], v[12:13]
	v_add_f32_e32 v3, 1.0, v3
	v_rcp_f32_e32 v14, v3
	v_mul_f32_e32 v3, 0xbfb8aa3b, v13
	v_exp_f32_e32 v3, v3
	s_nop 0
	v_add_f32_e32 v3, 1.0, v3
	v_rcp_f32_e32 v15, v3
	s_nop 0
	v_pk_mul_f32 v[12:13], v[16:17], v[14:15]
	s_nop 0
	v_cvt_pk_bf16_f32 v9, v12, v13
	v_add_u32_e32 v12, 32, v2
	v_ashrrev_i32_e32 v13, 31, v12
	global_store_dwordx4 v[20:21], v[6:9], off offset:2048
	v_lshl_add_u32 v3, v12, 9, v10
	s_nop 0
	v_lshl_add_u64 v[6:7], s[4:5], 0, v[12:13]
	v_mad_u64_u32 v[8:9], s[6:7], v6, s35, v[4:5]
	v_mov_b32_e32 v6, v9
	v_mad_u64_u32 v[6:7], s[6:7], v7, s35, v[6:7]
	v_mov_b32_e32 v9, v6
	v_lshl_add_u64 v[6:7], v[8:9], 0, s[18:19]
	v_lshl_add_u64 v[6:7], v[6:7], 0, v[0:1]
	v_add_co_u32_e32 v20, vcc, s31, v6
	s_nop 1
	v_addc_co_u32_e32 v21, vcc, 0, v7, vcc
	ds_read_b128 v[12:15], v3
	ds_read_b128 v[16:19], v3 offset:16
	s_waitcnt vmcnt(3)
	v_mov_b64_e32 v[6:7], v[84:85]
	v_mov_b64_e32 v[8:9], v[86:87]
	v_lshlrev_b32_e32 v22, 16, v6
	v_mul_f32_e32 v3, 0xbfb8aa3b, v22
	v_exp_f32_e32 v3, v3
	v_and_b32_e32 v23, 0xffff0000, v6
	s_waitcnt lgkmcnt(1)
	v_pk_mul_f32 v[12:13], v[12:13], v[22:23]
	v_add_f32_e32 v3, 1.0, v3
	v_rcp_f32_e32 v24, v3
	v_mul_f32_e32 v3, 0xbfb8aa3b, v23
	v_exp_f32_e32 v3, v3
	s_nop 0
	v_add_f32_e32 v3, 1.0, v3
	v_rcp_f32_e32 v25, v3
	s_nop 0
	v_pk_mul_f32 v[12:13], v[12:13], v[24:25]
	s_nop 0
	v_cvt_pk_bf16_f32 v6, v12, v13
	v_lshlrev_b32_e32 v12, 16, v7
	v_mul_f32_e32 v3, 0xbfb8aa3b, v12
	v_exp_f32_e32 v3, v3
	v_and_b32_e32 v13, 0xffff0000, v7
	v_pk_mul_f32 v[14:15], v[14:15], v[12:13]
	v_add_f32_e32 v3, 1.0, v3
	v_rcp_f32_e32 v22, v3
	v_mul_f32_e32 v3, 0xbfb8aa3b, v13
	v_exp_f32_e32 v3, v3
	s_nop 0
	v_add_f32_e32 v3, 1.0, v3
	v_rcp_f32_e32 v23, v3
	s_nop 0
	v_pk_mul_f32 v[12:13], v[14:15], v[22:23]
	s_nop 0
	v_cvt_pk_bf16_f32 v7, v12, v13
	v_lshlrev_b32_e32 v12, 16, v8
	v_mul_f32_e32 v3, 0xbfb8aa3b, v12
	v_exp_f32_e32 v3, v3
	v_and_b32_e32 v13, 0xffff0000, v8
	s_waitcnt lgkmcnt(0)
; __device__ __forceinline__ unsigned cvt_pk_bf16(float lo, float hi) { f32x2 v = {lo, hi}; bf16x2_t b = __builtin_convertvector(v, bf16x2_t); return __builtin_bit_cast(unsigned, b); }
; __device__ __forceinline__ float bf_lo(unsigned w) { return __uint_as_float(w << 16); }
; __device__ __forceinline__ float bf_hi(unsigned w) { return __uint_as_float(w & 0xffff0000u); }
; __device__ __forceinline__ float sigmoidf_fast(float x) { return __builtin_amdgcn_rcpf(1.0f + __builtin_amdgcn_exp2f(-1.4426950408889634f * x)); }
; #define LAS __attribute__((address_space(3)))
; __device__ __forceinline__ void attn_unit(LAS unsigned char* lds, bf16_t* Zg, const unsigned char* KVg, int S, int b, int h, int qb, const float* lq1, const float* lk1, const float* lq2, const float* lk2, const float* subln_g, const float* rel_bias, bool dostore = true) {
;     ...
; #pragma unroll
;     for (int i = 0; i < 4; ++i) { const int p = (tid >> 4) + 32 * i, c8 = (tid & 15) * 8; bf16_t* zp = Zg + (rowbase + q0 + p) * ZLD + COL_GA + h * 128 + c8;
;         const u32x4 gw = *(const u32x4*)zp; const f32x4 s0 = *(const LAS f32x4*)(exch + p * 128 + c8), s1 = *(const LAS f32x4*)(exch + p * 128 + c8 + 4);
;         const float sv[8] = {s0.x, s0.y, s0.z, s0.w, s1.x, s1.y, s1.z, s1.w}; u32x4 ow;
; #pragma unroll
;         for (int e = 0; e < 4; ++e) { const float g0 = bf_lo(gw[e]), g1 = bf_hi(gw[e]); ow[e] = cvt_pk_bf16(sv[2 * e] * g0 * sigmoidf_fast(g0), sv[2 * e + 1] * g1 * sigmoidf_fast(g1)); }
;         if (dostore) *(u32x4*)zp = ow; }
;     __syncthreads();
	v_pk_mul_f32 v[16:17], v[16:17], v[12:13]
	v_add_f32_e32 v3, 1.0, v3
	v_rcp_f32_e32 v14, v3
	v_mul_f32_e32 v3, 0xbfb8aa3b, v13
	v_exp_f32_e32 v3, v3
	s_nop 0
	v_add_f32_e32 v3, 1.0, v3
	v_rcp_f32_e32 v15, v3
	s_nop 0
	v_pk_mul_f32 v[12:13], v[16:17], v[14:15]
	s_nop 0
	v_cvt_pk_bf16_f32 v8, v12, v13
	v_lshlrev_b32_e32 v12, 16, v9
	v_mul_f32_e32 v3, 0xbfb8aa3b, v12
	v_exp_f32_e32 v3, v3
	v_and_b32_e32 v13, 0xffff0000, v9
	v_pk_mul_f32 v[16:17], v[18:19], v[12:13]
	v_add_f32_e32 v3, 1.0, v3
	v_rcp_f32_e32 v14, v3
	v_mul_f32_e32 v3, 0xbfb8aa3b, v13
	v_exp_f32_e32 v3, v3
	s_nop 0
	v_add_f32_e32 v3, 1.0, v3
	v_rcp_f32_e32 v15, v3
	s_nop 0
	v_pk_mul_f32 v[12:13], v[16:17], v[14:15]
	s_nop 0
	v_cvt_pk_bf16_f32 v9, v12, v13
	v_add_u32_e32 v12, 64, v2
	v_ashrrev_i32_e32 v13, 31, v12
	global_store_dwordx4 v[20:21], v[6:9], off offset:2048
	v_lshl_add_u32 v3, v12, 9, v10
	s_nop 0
	v_lshl_add_u64 v[6:7], s[4:5], 0, v[12:13]
	v_mad_u64_u32 v[8:9], s[6:7], v6, s35, v[4:5]
	v_mov_b32_e32 v6, v9
	v_mad_u64_u32 v[6:7], s[6:7], v7, s35, v[6:7]
	v_mov_b32_e32 v9, v6
	v_lshl_add_u64 v[6:7], v[8:9], 0, s[18:19]
	v_lshl_add_u64 v[6:7], v[6:7], 0, v[0:1]
	v_add_co_u32_e32 v20, vcc, s31, v6
	s_nop 1
	v_addc_co_u32_e32 v21, vcc, 0, v7, vcc
	ds_read_b128 v[12:15], v3
	ds_read_b128 v[16:19], v3 offset:16
	s_waitcnt vmcnt(3)
	v_mov_b64_e32 v[6:7], v[88:89]
	v_mov_b64_e32 v[8:9], v[90:91]
	v_lshlrev_b32_e32 v22, 16, v6
	v_mul_f32_e32 v3, 0xbfb8aa3b, v22
	v_exp_f32_e32 v3, v3
	v_and_b32_e32 v23, 0xffff0000, v6
	s_waitcnt lgkmcnt(1)
	v_pk_mul_f32 v[12:13], v[12:13], v[22:23]
	v_add_f32_e32 v3, 1.0, v3
	v_rcp_f32_e32 v24, v3
	v_mul_f32_e32 v3, 0xbfb8aa3b, v23
	v_exp_f32_e32 v3, v3
	s_nop 0
	v_add_f32_e32 v3, 1.0, v3
	v_rcp_f32_e32 v25, v3
	s_nop 0
	v_pk_mul_f32 v[12:13], v[12:13], v[24:25]
	s_nop 0
	v_cvt_pk_bf16_f32 v6, v12, v13
	v_lshlrev_b32_e32 v12, 16, v7
	v_mul_f32_e32 v3, 0xbfb8aa3b, v12
	v_exp_f32_e32 v3, v3
	v_and_b32_e32 v13, 0xffff0000, v7
	v_pk_mul_f32 v[14:15], v[14:15], v[12:13]
	v_add_f32_e32 v3, 1.0, v3
	v_rcp_f32_e32 v22, v3
	v_mul_f32_e32 v3, 0xbfb8aa3b, v13
	v_exp_f32_e32 v3, v3
	s_nop 0
	v_add_f32_e32 v3, 1.0, v3
	v_rcp_f32_e32 v23, v3
	s_nop 0
	v_pk_mul_f32 v[12:13], v[14:15], v[22:23]
	s_nop 0
	v_cvt_pk_bf16_f32 v7, v12, v13
	v_lshlrev_b32_e32 v12, 16, v8
	v_mul_f32_e32 v3, 0xbfb8aa3b, v12
	v_exp_f32_e32 v3, v3
	v_and_b32_e32 v13, 0xffff0000, v8
	s_waitcnt lgkmcnt(0)
	v_pk_mul_f32 v[16:17], v[16:17], v[12:13]
	v_add_f32_e32 v3, 1.0, v3
	v_rcp_f32_e32 v14, v3
	v_mul_f32_e32 v3, 0xbfb8aa3b, v13
	v_exp_f32_e32 v3, v3
	s_nop 0
	v_add_f32_e32 v3, 1.0, v3
	v_rcp_f32_e32 v15, v3
	s_nop 0
	v_pk_mul_f32 v[12:13], v[16:17], v[14:15]
	s_nop 0
	v_cvt_pk_bf16_f32 v8, v12, v13
	v_lshlrev_b32_e32 v12, 16, v9
	v_mul_f32_e32 v3, 0xbfb8aa3b, v12
	v_exp_f32_e32 v3, v3
	v_and_b32_e32 v13, 0xffff0000, v9
	v_pk_mul_f32 v[16:17], v[18:19], v[12:13]
	v_add_f32_e32 v3, 1.0, v3
	v_rcp_f32_e32 v14, v3
	v_mul_f32_e32 v3, 0xbfb8aa3b, v13
	v_exp_f32_e32 v3, v3
	s_nop 0
	v_add_f32_e32 v3, 1.0, v3
	v_rcp_f32_e32 v15, v3
	s_nop 0
	v_pk_mul_f32 v[12:13], v[16:17], v[14:15]
	s_nop 0
	v_cvt_pk_bf16_f32 v9, v12, v13
	global_store_dwordx4 v[20:21], v[6:9], off offset:2048
	s_nop 1
	v_add_u32_e32 v8, 0x60, v2
	v_ashrrev_i32_e32 v9, 31, v8
	v_lshl_add_u64 v[2:3], s[4:5], 0, v[8:9]
	v_mad_u64_u32 v[4:5], s[4:5], v2, s35, v[4:5]
	v_mov_b32_e32 v2, v5
	v_mad_u64_u32 v[2:3], s[4:5], v3, s35, v[2:3]
	v_mov_b32_e32 v5, v2
	v_lshl_add_u64 v[2:3], v[4:5], 0, s[18:19]
	v_lshl_add_u64 v[2:3], v[2:3], 0, v[0:1]
	v_add_co_u32_e32 v6, vcc, s31, v2
	v_lshl_add_u32 v0, v8, 9, v10
	s_nop 0
	v_addc_co_u32_e32 v7, vcc, 0, v3, vcc
	ds_read_b128 v[8:11], v0
	ds_read_b128 v[12:15], v0 offset:16
	s_waitcnt vmcnt(3)
	v_mov_b64_e32 v[2:3], v[92:93]
	v_mov_b64_e32 v[4:5], v[94:95]
	v_lshlrev_b32_e32 v16, 16, v2
	v_mul_f32_e32 v0, 0xbfb8aa3b, v16
	v_exp_f32_e32 v0, v0
	v_and_b32_e32 v17, 0xffff0000, v2
	s_waitcnt lgkmcnt(1)
	v_pk_mul_f32 v[8:9], v[8:9], v[16:17]
	v_add_f32_e32 v0, 1.0, v0
	v_rcp_f32_e32 v18, v0
	v_mul_f32_e32 v0, 0xbfb8aa3b, v17
	v_exp_f32_e32 v0, v0
	s_nop 0
	v_add_f32_e32 v0, 1.0, v0
	v_rcp_f32_e32 v19, v0
	s_nop 0
	v_pk_mul_f32 v[8:9], v[8:9], v[18:19]
	s_nop 0
	v_cvt_pk_bf16_f32 v2, v8, v9
	v_lshlrev_b32_e32 v8, 16, v3
	v_mul_f32_e32 v0, 0xbfb8aa3b, v8
	v_exp_f32_e32 v0, v0
	v_and_b32_e32 v9, 0xffff0000, v3
	v_pk_mul_f32 v[10:11], v[10:11], v[8:9]
	v_add_f32_e32 v0, 1.0, v0
	v_rcp_f32_e32 v16, v0
	v_mul_f32_e32 v0, 0xbfb8aa3b, v9
	v_exp_f32_e32 v0, v0
	s_nop 0
	v_add_f32_e32 v0, 1.0, v0
	v_rcp_f32_e32 v17, v0
	s_nop 0
	v_pk_mul_f32 v[8:9], v[10:11], v[16:17]
	s_nop 0
	v_cvt_pk_bf16_f32 v3, v8, v9
	v_lshlrev_b32_e32 v8, 16, v4
	v_mul_f32_e32 v0, 0xbfb8aa3b, v8
	v_exp_f32_e32 v0, v0
	v_and_b32_e32 v9, 0xffff0000, v4
	s_waitcnt lgkmcnt(0)
	v_pk_mul_f32 v[12:13], v[12:13], v[8:9]
	v_add_f32_e32 v0, 1.0, v0
	v_rcp_f32_e32 v10, v0
	v_mul_f32_e32 v0, 0xbfb8aa3b, v9
	v_exp_f32_e32 v0, v0
	s_nop 0
	v_add_f32_e32 v0, 1.0, v0
	v_rcp_f32_e32 v11, v0
	s_nop 0
	v_pk_mul_f32 v[8:9], v[12:13], v[10:11]
	s_nop 0
	v_cvt_pk_bf16_f32 v4, v8, v9
	v_lshlrev_b32_e32 v8, 16, v5
	v_mul_f32_e32 v0, 0xbfb8aa3b, v8
	v_exp_f32_e32 v0, v0
	v_and_b32_e32 v9, 0xffff0000, v5
	v_pk_mul_f32 v[12:13], v[14:15], v[8:9]
	v_add_f32_e32 v0, 1.0, v0
	v_rcp_f32_e32 v10, v0
	v_mul_f32_e32 v0, 0xbfb8aa3b, v9
	v_exp_f32_e32 v0, v0
	s_nop 0
	v_add_f32_e32 v0, 1.0, v0
	v_rcp_f32_e32 v11, v0
	s_nop 0
	v_pk_mul_f32 v[8:9], v[12:13], v[10:11]
	s_nop 0
	v_cvt_pk_bf16_f32 v5, v8, v9
	global_store_dwordx4 v[6:7], v[2:5], off offset:2048
	s_barrier
	s_cbranch_scc0 .LBB0_290

; __device__ __forceinline__ float bf_lo(unsigned w) { return __uint_as_float(w << 16); }
; __device__ __forceinline__ float bf_hi(unsigned w) { return __uint_as_float(w & 0xffff0000u); }
;     __device__ __forceinline__ void operator()(f32x4 (&acc)[2][2][4][2], const Unit& u, int wr, int wc, int fr, int fq) const {
;     ...
;             for (int m = 0; m < 4; ++m) { const int r = row0 + ai * HALF + m * 16;
; #pragma unroll
;                 for (int bj = 0; bj < 2; ++bj) { const int c = col0 + bj * HALF;
;                     const u32x4 gb = *(const u32x4*)(Gb + (size_t)r * ldg + c);
;                     float eb[8];
; #pragma unroll
;                     for (int e = 0; e < 4; ++e) { eb[2 * e] = __builtin_amdgcn_exp2f(-1.4426950408889634f * bf_lo(gb[e])); eb[2 * e + 1] = __builtin_amdgcn_exp2f(-1.4426950408889634f * bf_hi(gb[e])); }
;                     if (u.half == 0) { const u32x4 ga = *(const u32x4*)(Ga + (size_t)r * ldg + c);
; #pragma unroll
;                         for (int e = 0; e < 4; ++e) { const float ea0 = __builtin_amdgcn_exp2f(-1.4426950408889634f * bf_lo(ga[e])), ea1 = __builtin_amdgcn_exp2f(-1.4426950408889634f * bf_hi(ga[e]));
;                             acc[ai][bj][m][e >> 1][(2 * e) & 3] *= (1.0f + eb[2 * e]) * __builtin_amdgcn_rcpf(1.0f + ea0);
;                             acc[ai][bj][m][e >> 1][(2 * e + 1) & 3] *= (1.0f + eb[2 * e + 1]) * __builtin_amdgcn_rcpf(1.0f + ea1); } }
.LBB0_322:
	v_lshl_add_u32 v132, s31, 8, v152
	v_lshl_or_b32 v2, s30, 8, v153
	v_mad_i64_i32 v[138:139], s[8:9], v132, s90, 0
	v_lshl_add_u64 v[134:135], v[138:139], 1, s[72:73]
	v_ashrrev_i32_e32 v3, 31, v2
	v_lshl_add_u64 v[136:137], v[2:3], 1, v[134:135]
	global_load_dwordx4 v[140:143], v[136:137], off
	global_load_dwordx4 v[162:165], v[136:137], off offset:256
	v_add_co_u32_e32 v226, vcc, 0x48000, v136
	s_nop 1
	v_addc_co_u32_e32 v227, vcc, 0, v137, vcc
	global_load_dwordx4 v[166:169], v[226:227], off
	global_load_dwordx4 v[170:173], v[226:227], off offset:256
	v_add_co_u32_e32 v226, vcc, 0x90000, v136
	s_nop 1
	v_addc_co_u32_e32 v227, vcc, 0, v137, vcc
	global_load_dwordx4 v[174:177], v[226:227], off
	global_load_dwordx4 v[178:181], v[226:227], off offset:256
	v_add_co_u32_e32 v226, vcc, 0xd8000, v136
	s_nop 1
	v_addc_co_u32_e32 v227, vcc, 0, v137, vcc
	global_load_dwordx4 v[182:185], v[226:227], off
	global_load_dwordx4 v[186:189], v[226:227], off offset:256
	v_add_co_u32_e32 v226, vcc, 0x240000, v136
	s_nop 1
	v_addc_co_u32_e32 v227, vcc, 0, v137, vcc
	global_load_dwordx4 v[190:193], v[226:227], off
	global_load_dwordx4 v[210:213], v[226:227], off offset:256
	v_add_co_u32_e32 v226, vcc, 0x288000, v136
	s_nop 1
	v_addc_co_u32_e32 v227, vcc, 0, v137, vcc
	global_load_dwordx4 v[214:217], v[226:227], off
	global_load_dwordx4 v[218:221], v[226:227], off offset:256
	v_add_co_u32_e32 v226, vcc, 0x2d0000, v136
	s_nop 1
	v_addc_co_u32_e32 v227, vcc, 0, v137, vcc
	global_load_dwordx4 v[222:225], v[226:227], off
	global_load_dwordx4 v[230:233], v[226:227], off offset:256
	v_add_co_u32_e32 v226, vcc, 0x318000, v136
	s_nop 1
	v_addc_co_u32_e32 v227, vcc, 0, v137, vcc
	global_load_dwordx4 v[234:237], v[226:227], off
	v_ashrrev_i32_e32 v133, 31, v132
	s_cmp_lg_u32 s10, 0
	s_cselect_b64 s[26:27], -1, 0
	s_cmp_eq_u32 s10, 0
	s_waitcnt vmcnt(14)
	v_lshlrev_b32_e32 v0, 16, v140
	v_and_b32_e32 v134, 0xffff0000, v140
	v_lshlrev_b32_e32 v135, 16, v141
	v_and_b32_e32 v140, 0xffff0000, v141
	v_lshlrev_b32_e32 v141, 16, v142
	v_and_b32_e32 v142, 0xffff0000, v142
	v_lshlrev_b32_e32 v144, 16, v143
	v_and_b32_e32 v143, 0xffff0000, v143
	v_mul_f32_e32 v0, 0xbfb8aa3b, v0
	v_mul_f32_e32 v134, 0xbfb8aa3b, v134
	v_mul_f32_e32 v135, 0xbfb8aa3b, v135
	v_mul_f32_e32 v140, 0xbfb8aa3b, v140
	v_mul_f32_e32 v141, 0xbfb8aa3b, v141
	v_mul_f32_e32 v142, 0xbfb8aa3b, v142
	v_mul_f32_e32 v156, 0xbfb8aa3b, v144
	v_mul_f32_e32 v143, 0xbfb8aa3b, v143
	v_exp_f32_e32 v144, v0
	v_exp_f32_e32 v145, v134
	v_exp_f32_e32 v146, v135
	v_exp_f32_e32 v147, v140
	v_exp_f32_e32 v140, v141
	v_exp_f32_e32 v141, v142
	v_exp_f32_e32 v142, v156
	v_exp_f32_e32 v143, v143
	v_lshlrev_b64 v[134:135], 11, v[132:133]
	v_lshl_add_u64 v[134:135], s[74:75], 0, v[134:135]
	s_cbranch_scc1 .LBB0_373
	v_add_f32_e32 v0, 1.0, v144
	v_rcp_f32_e32 v156, v0
	v_add_f32_e32 v0, 1.0, v145
	v_rcp_f32_e32 v157, v0
	v_add_f32_e32 v0, 1.0, v146
	v_rcp_f32_e32 v158, v0
	v_add_f32_e32 v0, 1.0, v147
	v_rcp_f32_e32 v159, v0
	v_pk_mul_f32 v[156:157], v[128:129], v[156:157]
	v_add_f32_e32 v0, 1.0, v140
	v_cvt_pk_bf16_f32 v156, v156, v157
	v_pk_mul_f32 v[158:159], v[130:131], v[158:159]
	s_nop 0
	v_cvt_pk_bf16_f32 v157, v158, v159
	v_rcp_f32_e32 v158, v0
	v_add_f32_e32 v0, 1.0, v141
	v_rcp_f32_e32 v159, v0
	v_add_f32_e32 v0, 1.0, v142
	v_rcp_f32_e32 v160, v0
	v_add_f32_e32 v0, 1.0, v143
	v_rcp_f32_e32 v161, v0
	v_pk_mul_f32 v[158:159], v[124:125], v[158:159]
	v_pk_mul_f32 v[160:161], v[126:127], v[160:161]
	v_cvt_pk_bf16_f32 v158, v158, v159
	v_cvt_pk_bf16_f32 v159, v160, v161
	v_lshl_add_u64 v[160:161], v[2:3], 1, v[134:135]
	global_store_dwordx4 v[160:161], v[156:159], off
	v_lshl_add_u64 v[138:139], v[138:139], 1, s[70:71]
	s_cbranch_execnz .LBB0_325

; __device__ __forceinline__ unsigned cvt_pk_bf16(float lo, float hi) { f32x2 v = {lo, hi}; bf16x2_t b = __builtin_convertvector(v, bf16x2_t); return __builtin_bit_cast(unsigned, b); }
; __device__ __forceinline__ float bf_lo(unsigned w) { return __uint_as_float(w << 16); }
; __device__ __forceinline__ float bf_hi(unsigned w) { return __uint_as_float(w & 0xffff0000u); }
;     __device__ __forceinline__ void operator()(f32x4 (&acc)[2][2][4][2], const Unit& u, int wr, int wc, int fr, int fq) const {
;     ...
;                 for (int bj = 0; bj < 2; ++bj) { const int c = col0 + bj * HALF;
;                     const u32x4 gb = *(const u32x4*)(Gb + (size_t)r * ldg + c);
;                     float eb[8];
; #pragma unroll
;                     for (int e = 0; e < 4; ++e) { eb[2 * e] = __builtin_amdgcn_exp2f(-1.4426950408889634f * bf_lo(gb[e])); eb[2 * e + 1] = __builtin_amdgcn_exp2f(-1.4426950408889634f * bf_hi(gb[e])); }
;                     if (u.half == 0) { const u32x4 ga = *(const u32x4*)(Ga + (size_t)r * ldg + c);
; #pragma unroll
;                         for (int e = 0; e < 4; ++e) { const float ea0 = __builtin_amdgcn_exp2f(-1.4426950408889634f * bf_lo(ga[e])), ea1 = __builtin_amdgcn_exp2f(-1.4426950408889634f * bf_hi(ga[e]));
;                             acc[ai][bj][m][e >> 1][(2 * e) & 3] *= (1.0f + eb[2 * e]) * __builtin_amdgcn_rcpf(1.0f + ea0);
;                             acc[ai][bj][m][e >> 1][(2 * e + 1) & 3] *= (1.0f + eb[2 * e + 1]) * __builtin_amdgcn_rcpf(1.0f + ea1); } }
;                     else { u32x4 w;
; #pragma unroll
;                         for (int e = 0; e < 4; ++e) { const float a0 = acc[ai][bj][m][e >> 1][(2 * e) & 3] * __builtin_amdgcn_rcpf(1.0f + eb[2 * e]), a1 = acc[ai][bj][m][e >> 1][(2 * e + 1) & 3] * __builtin_amdgcn_rcpf(1.0f + eb[2 * e + 1]);
;                             w[e] = cvt_pk_bf16(a0, a1); }
;                         *(u32x4*)(O + (size_t)r * ldo + c) = w; } } }
.LBB0_325:
	s_andn2_b64 vcc, exec, s[26:27]
	s_waitcnt vmcnt(14)
	v_mov_b64_e32 v[140:141], v[162:163]
	v_mov_b64_e32 v[142:143], v[164:165]
	v_lshlrev_b32_e32 v0, 16, v140
	v_and_b32_e32 v133, 0xffff0000, v140
	v_lshlrev_b32_e32 v136, 16, v141
	v_and_b32_e32 v137, 0xffff0000, v141
	v_lshlrev_b32_e32 v140, 16, v142
	v_and_b32_e32 v141, 0xffff0000, v142
	v_lshlrev_b32_e32 v142, 16, v143
	v_and_b32_e32 v143, 0xffff0000, v143
	v_mul_f32_e32 v0, 0xbfb8aa3b, v0
	v_mul_f32_e32 v133, 0xbfb8aa3b, v133
	v_mul_f32_e32 v136, 0xbfb8aa3b, v136
	v_mul_f32_e32 v137, 0xbfb8aa3b, v137
	v_mul_f32_e32 v140, 0xbfb8aa3b, v140
	v_mul_f32_e32 v141, 0xbfb8aa3b, v141
	v_mul_f32_e32 v146, 0xbfb8aa3b, v142
	v_mul_f32_e32 v147, 0xbfb8aa3b, v143
	v_exp_f32_e32 v142, v0
	v_exp_f32_e32 v143, v133
	v_exp_f32_e32 v144, v136
	v_exp_f32_e32 v145, v137
	v_exp_f32_e32 v136, v140
	v_exp_f32_e32 v137, v141
	v_exp_f32_e32 v140, v146
	v_exp_f32_e32 v141, v147
	v_cndmask_b32_e64 v0, 0, 1, s[26:27]
	v_cmp_ne_u32_e64 s[8:9], 1, v0
	s_cbranch_vccnz .LBB0_374
	v_add_f32_e32 v0, 1.0, v142
	v_rcp_f32_e32 v146, v0
	v_add_f32_e32 v0, 1.0, v143
	v_rcp_f32_e32 v147, v0
	v_add_f32_e32 v0, 1.0, v144
	v_lshl_add_u64 v[134:135], v[2:3], 1, v[134:135]
	v_pk_mul_f32 v[146:147], v[96:97], v[146:147]
	s_nop 0
	v_cvt_pk_bf16_f32 v156, v146, v147
	v_rcp_f32_e32 v146, v0
	v_add_f32_e32 v0, 1.0, v145
	v_rcp_f32_e32 v147, v0
	v_add_f32_e32 v0, 1.0, v136
	v_pk_mul_f32 v[146:147], v[98:99], v[146:147]
	s_nop 0
	v_cvt_pk_bf16_f32 v157, v146, v147
	v_rcp_f32_e32 v146, v0
	v_add_f32_e32 v0, 1.0, v137
	v_rcp_f32_e32 v147, v0
	v_add_f32_e32 v0, 1.0, v140
	v_pk_mul_f32 v[146:147], v[92:93], v[146:147]
	s_nop 0
	v_cvt_pk_bf16_f32 v158, v146, v147
	v_rcp_f32_e32 v146, v0
	v_add_f32_e32 v0, 1.0, v141
	v_rcp_f32_e32 v147, v0
	s_nop 0
	v_pk_mul_f32 v[146:147], v[94:95], v[146:147]
	s_nop 0
	v_cvt_pk_bf16_f32 v159, v146, v147
	global_store_dwordx4 v[134:135], v[156:159], off offset:256
	s_cbranch_execnz .LBB0_328

; __device__ __forceinline__ unsigned cvt_pk_bf16(float lo, float hi) { f32x2 v = {lo, hi}; bf16x2_t b = __builtin_convertvector(v, bf16x2_t); return __builtin_bit_cast(unsigned, b); }
; __device__ __forceinline__ float bf_lo(unsigned w) { return __uint_as_float(w << 16); }
; __device__ __forceinline__ float bf_hi(unsigned w) { return __uint_as_float(w & 0xffff0000u); }
;     __device__ __forceinline__ void operator()(f32x4 (&acc)[2][2][4][2], const Unit& u, int wr, int wc, int fr, int fq) const {
;     ...
;                 for (int bj = 0; bj < 2; ++bj) { const int c = col0 + bj * HALF;
;                     const u32x4 gb = *(const u32x4*)(Gb + (size_t)r * ldg + c);
;                     float eb[8];
; #pragma unroll
;                     for (int e = 0; e < 4; ++e) { eb[2 * e] = __builtin_amdgcn_exp2f(-1.4426950408889634f * bf_lo(gb[e])); eb[2 * e + 1] = __builtin_amdgcn_exp2f(-1.4426950408889634f * bf_hi(gb[e])); }
;                     if (u.half == 0) { const u32x4 ga = *(const u32x4*)(Ga + (size_t)r * ldg + c);
; #pragma unroll
;                         for (int e = 0; e < 4; ++e) { const float ea0 = __builtin_amdgcn_exp2f(-1.4426950408889634f * bf_lo(ga[e])), ea1 = __builtin_amdgcn_exp2f(-1.4426950408889634f * bf_hi(ga[e]));
;                             acc[ai][bj][m][e >> 1][(2 * e) & 3] *= (1.0f + eb[2 * e]) * __builtin_amdgcn_rcpf(1.0f + ea0);
;                             acc[ai][bj][m][e >> 1][(2 * e + 1) & 3] *= (1.0f + eb[2 * e + 1]) * __builtin_amdgcn_rcpf(1.0f + ea1); } }
;                     else { u32x4 w;
; #pragma unroll
;                         for (int e = 0; e < 4; ++e) { const float a0 = acc[ai][bj][m][e >> 1][(2 * e) & 3] * __builtin_amdgcn_rcpf(1.0f + eb[2 * e]), a1 = acc[ai][bj][m][e >> 1][(2 * e + 1) & 3] * __builtin_amdgcn_rcpf(1.0f + eb[2 * e + 1]);
;                             w[e] = cvt_pk_bf16(a0, a1); }
;                         *(u32x4*)(O + (size_t)r * ldo + c) = w; } } }
.LBB0_328:
	v_or_b32_e32 v134, 16, v132
	v_mad_i64_i32 v[138:139], s[26:27], v134, s90, 0
	v_lshl_add_u64 v[136:137], v[138:139], 1, s[72:73]
	v_lshl_add_u64 v[136:137], v[2:3], 1, v[136:137]
	v_ashrrev_i32_e32 v135, 31, v134
	v_lshlrev_b64 v[134:135], 11, v[134:135]
	s_and_b64 vcc, exec, s[8:9]
	v_lshl_add_u64 v[134:135], s[74:75], 0, v[134:135]
	s_waitcnt vmcnt(14)
	v_mov_b64_e32 v[140:141], v[166:167]
	v_mov_b64_e32 v[142:143], v[168:169]
	v_lshlrev_b32_e32 v0, 16, v140
	v_and_b32_e32 v133, 0xffff0000, v140
	v_lshlrev_b32_e32 v140, 16, v141
	v_and_b32_e32 v141, 0xffff0000, v141
	v_lshlrev_b32_e32 v144, 16, v142
	v_and_b32_e32 v142, 0xffff0000, v142
	v_lshlrev_b32_e32 v145, 16, v143
	v_and_b32_e32 v143, 0xffff0000, v143
	v_mul_f32_e32 v0, 0xbfb8aa3b, v0
	v_mul_f32_e32 v133, 0xbfb8aa3b, v133
	v_mul_f32_e32 v140, 0xbfb8aa3b, v140
	v_mul_f32_e32 v141, 0xbfb8aa3b, v141
	v_mul_f32_e32 v156, 0xbfb8aa3b, v144
	v_mul_f32_e32 v142, 0xbfb8aa3b, v142
	v_mul_f32_e32 v157, 0xbfb8aa3b, v145
	v_mul_f32_e32 v143, 0xbfb8aa3b, v143
	v_exp_f32_e32 v144, v0
	v_exp_f32_e32 v145, v133
	v_exp_f32_e32 v146, v140
	v_exp_f32_e32 v147, v141
	v_exp_f32_e32 v140, v156
	v_exp_f32_e32 v141, v142
	v_exp_f32_e32 v142, v157
	v_exp_f32_e32 v143, v143
	s_cbranch_vccnz .LBB0_375
	v_add_f32_e32 v0, 1.0, v144
	v_rcp_f32_e32 v156, v0
	v_add_f32_e32 v0, 1.0, v145
	v_rcp_f32_e32 v157, v0
	v_add_f32_e32 v0, 1.0, v146
	v_rcp_f32_e32 v158, v0
	v_add_f32_e32 v0, 1.0, v147
	v_rcp_f32_e32 v159, v0
	v_pk_mul_f32 v[156:157], v[120:121], v[156:157]
	v_add_f32_e32 v0, 1.0, v140
	v_cvt_pk_bf16_f32 v156, v156, v157
	v_pk_mul_f32 v[158:159], v[122:123], v[158:159]
	s_nop 0
	v_cvt_pk_bf16_f32 v157, v158, v159
	v_rcp_f32_e32 v158, v0
	v_add_f32_e32 v0, 1.0, v141
	v_rcp_f32_e32 v159, v0
	v_add_f32_e32 v0, 1.0, v142
	v_rcp_f32_e32 v160, v0
	v_add_f32_e32 v0, 1.0, v143
	v_rcp_f32_e32 v161, v0
	v_pk_mul_f32 v[158:159], v[116:117], v[158:159]
	v_pk_mul_f32 v[160:161], v[118:119], v[160:161]
	v_cvt_pk_bf16_f32 v158, v158, v159
	v_cvt_pk_bf16_f32 v159, v160, v161
	v_lshl_add_u64 v[160:161], v[2:3], 1, v[134:135]
	global_store_dwordx4 v[160:161], v[156:159], off
	v_lshl_add_u64 v[138:139], v[138:139], 1, s[70:71]
	s_cbranch_execnz .LBB0_331

; __device__ __forceinline__ unsigned cvt_pk_bf16(float lo, float hi) { f32x2 v = {lo, hi}; bf16x2_t b = __builtin_convertvector(v, bf16x2_t); return __builtin_bit_cast(unsigned, b); }
; __device__ __forceinline__ float bf_lo(unsigned w) { return __uint_as_float(w << 16); }
; __device__ __forceinline__ float bf_hi(unsigned w) { return __uint_as_float(w & 0xffff0000u); }
;     __device__ __forceinline__ void operator()(f32x4 (&acc)[2][2][4][2], const Unit& u, int wr, int wc, int fr, int fq) const {
;     ...
;                 for (int bj = 0; bj < 2; ++bj) { const int c = col0 + bj * HALF;
;                     const u32x4 gb = *(const u32x4*)(Gb + (size_t)r * ldg + c);
;                     float eb[8];
; #pragma unroll
;                     for (int e = 0; e < 4; ++e) { eb[2 * e] = __builtin_amdgcn_exp2f(-1.4426950408889634f * bf_lo(gb[e])); eb[2 * e + 1] = __builtin_amdgcn_exp2f(-1.4426950408889634f * bf_hi(gb[e])); }
;                     if (u.half == 0) { const u32x4 ga = *(const u32x4*)(Ga + (size_t)r * ldg + c);
; #pragma unroll
;                         for (int e = 0; e < 4; ++e) { const float ea0 = __builtin_amdgcn_exp2f(-1.4426950408889634f * bf_lo(ga[e])), ea1 = __builtin_amdgcn_exp2f(-1.4426950408889634f * bf_hi(ga[e]));
;                             acc[ai][bj][m][e >> 1][(2 * e) & 3] *= (1.0f + eb[2 * e]) * __builtin_amdgcn_rcpf(1.0f + ea0);
;                             acc[ai][bj][m][e >> 1][(2 * e + 1) & 3] *= (1.0f + eb[2 * e + 1]) * __builtin_amdgcn_rcpf(1.0f + ea1); } }
;                     else { u32x4 w;
; #pragma unroll
;                         for (int e = 0; e < 4; ++e) { const float a0 = acc[ai][bj][m][e >> 1][(2 * e) & 3] * __builtin_amdgcn_rcpf(1.0f + eb[2 * e]), a1 = acc[ai][bj][m][e >> 1][(2 * e + 1) & 3] * __builtin_amdgcn_rcpf(1.0f + eb[2 * e + 1]);
;                             w[e] = cvt_pk_bf16(a0, a1); }
;                         *(u32x4*)(O + (size_t)r * ldo + c) = w; } } }
.LBB0_331:
	s_and_b64 vcc, exec, s[8:9]
	s_waitcnt vmcnt(14)
	v_mov_b64_e32 v[140:141], v[170:171]
	v_mov_b64_e32 v[142:143], v[172:173]
	v_lshlrev_b32_e32 v0, 16, v140
	v_and_b32_e32 v133, 0xffff0000, v140
	v_lshlrev_b32_e32 v136, 16, v141
	v_and_b32_e32 v137, 0xffff0000, v141
	v_lshlrev_b32_e32 v140, 16, v142
	v_and_b32_e32 v141, 0xffff0000, v142
	v_lshlrev_b32_e32 v142, 16, v143
	v_and_b32_e32 v143, 0xffff0000, v143
	v_mul_f32_e32 v0, 0xbfb8aa3b, v0
	v_mul_f32_e32 v133, 0xbfb8aa3b, v133
	v_mul_f32_e32 v136, 0xbfb8aa3b, v136
	v_mul_f32_e32 v137, 0xbfb8aa3b, v137
	v_mul_f32_e32 v140, 0xbfb8aa3b, v140
	v_mul_f32_e32 v141, 0xbfb8aa3b, v141
	v_mul_f32_e32 v146, 0xbfb8aa3b, v142
	v_mul_f32_e32 v147, 0xbfb8aa3b, v143
	v_exp_f32_e32 v142, v0
	v_exp_f32_e32 v143, v133
	v_exp_f32_e32 v144, v136
	v_exp_f32_e32 v145, v137
	v_exp_f32_e32 v136, v140
	v_exp_f32_e32 v137, v141
	v_exp_f32_e32 v140, v146
	v_exp_f32_e32 v141, v147
	s_cbranch_vccnz .LBB0_376
	v_add_f32_e32 v0, 1.0, v142
	v_rcp_f32_e32 v146, v0
	v_add_f32_e32 v0, 1.0, v143
	v_rcp_f32_e32 v147, v0
	v_add_f32_e32 v0, 1.0, v144
	v_lshl_add_u64 v[134:135], v[2:3], 1, v[134:135]
	v_pk_mul_f32 v[146:147], v[88:89], v[146:147]
	s_nop 0
	v_cvt_pk_bf16_f32 v156, v146, v147
	v_rcp_f32_e32 v146, v0
	v_add_f32_e32 v0, 1.0, v145
	v_rcp_f32_e32 v147, v0
	v_add_f32_e32 v0, 1.0, v136
	v_pk_mul_f32 v[146:147], v[90:91], v[146:147]
	s_nop 0
	v_cvt_pk_bf16_f32 v157, v146, v147
	v_rcp_f32_e32 v146, v0
	v_add_f32_e32 v0, 1.0, v137
	v_rcp_f32_e32 v147, v0
	v_add_f32_e32 v0, 1.0, v140
	v_pk_mul_f32 v[146:147], v[84:85], v[146:147]
	s_nop 0
	v_cvt_pk_bf16_f32 v158, v146, v147
	v_rcp_f32_e32 v146, v0
	v_add_f32_e32 v0, 1.0, v141
	v_rcp_f32_e32 v147, v0
	s_nop 0
	v_pk_mul_f32 v[146:147], v[86:87], v[146:147]
	s_nop 0
	v_cvt_pk_bf16_f32 v159, v146, v147
	global_store_dwordx4 v[134:135], v[156:159], off offset:256
	s_cbranch_execnz .LBB0_334

; __device__ __forceinline__ unsigned cvt_pk_bf16(float lo, float hi) { f32x2 v = {lo, hi}; bf16x2_t b = __builtin_convertvector(v, bf16x2_t); return __builtin_bit_cast(unsigned, b); }
; __device__ __forceinline__ float bf_lo(unsigned w) { return __uint_as_float(w << 16); }
; __device__ __forceinline__ float bf_hi(unsigned w) { return __uint_as_float(w & 0xffff0000u); }
;     __device__ __forceinline__ void operator()(f32x4 (&acc)[2][2][4][2], const Unit& u, int wr, int wc, int fr, int fq) const {
;     ...
;                 for (int bj = 0; bj < 2; ++bj) { const int c = col0 + bj * HALF;
;                     const u32x4 gb = *(const u32x4*)(Gb + (size_t)r * ldg + c);
;                     float eb[8];
; #pragma unroll
;                     for (int e = 0; e < 4; ++e) { eb[2 * e] = __builtin_amdgcn_exp2f(-1.4426950408889634f * bf_lo(gb[e])); eb[2 * e + 1] = __builtin_amdgcn_exp2f(-1.4426950408889634f * bf_hi(gb[e])); }
;                     if (u.half == 0) { const u32x4 ga = *(const u32x4*)(Ga + (size_t)r * ldg + c);
; #pragma unroll
;                         for (int e = 0; e < 4; ++e) { const float ea0 = __builtin_amdgcn_exp2f(-1.4426950408889634f * bf_lo(ga[e])), ea1 = __builtin_amdgcn_exp2f(-1.4426950408889634f * bf_hi(ga[e]));
;                             acc[ai][bj][m][e >> 1][(2 * e) & 3] *= (1.0f + eb[2 * e]) * __builtin_amdgcn_rcpf(1.0f + ea0);
;                             acc[ai][bj][m][e >> 1][(2 * e + 1) & 3] *= (1.0f + eb[2 * e + 1]) * __builtin_amdgcn_rcpf(1.0f + ea1); } }
;                     else { u32x4 w;
; #pragma unroll
;                         for (int e = 0; e < 4; ++e) { const float a0 = acc[ai][bj][m][e >> 1][(2 * e) & 3] * __builtin_amdgcn_rcpf(1.0f + eb[2 * e]), a1 = acc[ai][bj][m][e >> 1][(2 * e + 1) & 3] * __builtin_amdgcn_rcpf(1.0f + eb[2 * e + 1]);
;                             w[e] = cvt_pk_bf16(a0, a1); }
;                         *(u32x4*)(O + (size_t)r * ldo + c) = w; } } }
.LBB0_334:
	v_or_b32_e32 v134, 32, v132
	v_mad_i64_i32 v[138:139], s[26:27], v134, s90, 0
	v_lshl_add_u64 v[136:137], v[138:139], 1, s[72:73]
	v_lshl_add_u64 v[136:137], v[2:3], 1, v[136:137]
	v_ashrrev_i32_e32 v135, 31, v134
	v_lshlrev_b64 v[134:135], 11, v[134:135]
	s_and_b64 vcc, exec, s[8:9]
	v_lshl_add_u64 v[134:135], s[74:75], 0, v[134:135]
	s_waitcnt vmcnt(14)
	v_mov_b64_e32 v[140:141], v[174:175]
	v_mov_b64_e32 v[142:143], v[176:177]
	v_lshlrev_b32_e32 v0, 16, v140
	v_and_b32_e32 v133, 0xffff0000, v140
	v_lshlrev_b32_e32 v140, 16, v141
	v_and_b32_e32 v141, 0xffff0000, v141
	v_lshlrev_b32_e32 v144, 16, v142
	v_and_b32_e32 v142, 0xffff0000, v142
	v_lshlrev_b32_e32 v145, 16, v143
	v_and_b32_e32 v143, 0xffff0000, v143
	v_mul_f32_e32 v0, 0xbfb8aa3b, v0
	v_mul_f32_e32 v133, 0xbfb8aa3b, v133
	v_mul_f32_e32 v140, 0xbfb8aa3b, v140
	v_mul_f32_e32 v141, 0xbfb8aa3b, v141
	v_mul_f32_e32 v156, 0xbfb8aa3b, v144
	v_mul_f32_e32 v142, 0xbfb8aa3b, v142
	v_mul_f32_e32 v157, 0xbfb8aa3b, v145
	v_mul_f32_e32 v143, 0xbfb8aa3b, v143
	v_exp_f32_e32 v144, v0
	v_exp_f32_e32 v145, v133
	v_exp_f32_e32 v146, v140
	v_exp_f32_e32 v147, v141
	v_exp_f32_e32 v140, v156
	v_exp_f32_e32 v141, v142
	v_exp_f32_e32 v142, v157
	v_exp_f32_e32 v143, v143
	s_cbranch_vccnz .LBB0_377
	v_add_f32_e32 v0, 1.0, v144
	v_rcp_f32_e32 v156, v0
	v_add_f32_e32 v0, 1.0, v145
	v_rcp_f32_e32 v157, v0
	v_add_f32_e32 v0, 1.0, v146
	v_rcp_f32_e32 v158, v0
	v_add_f32_e32 v0, 1.0, v147
	v_rcp_f32_e32 v159, v0
	v_pk_mul_f32 v[156:157], v[112:113], v[156:157]
	v_add_f32_e32 v0, 1.0, v140
	v_cvt_pk_bf16_f32 v156, v156, v157
	v_pk_mul_f32 v[158:159], v[114:115], v[158:159]
	s_nop 0
	v_cvt_pk_bf16_f32 v157, v158, v159
	v_rcp_f32_e32 v158, v0
	v_add_f32_e32 v0, 1.0, v141
	v_rcp_f32_e32 v159, v0
	v_add_f32_e32 v0, 1.0, v142
	v_rcp_f32_e32 v160, v0
	v_add_f32_e32 v0, 1.0, v143
	v_rcp_f32_e32 v161, v0
	v_pk_mul_f32 v[158:159], v[108:109], v[158:159]
	v_pk_mul_f32 v[160:161], v[110:111], v[160:161]
	v_cvt_pk_bf16_f32 v158, v158, v159
	v_cvt_pk_bf16_f32 v159, v160, v161
	v_lshl_add_u64 v[160:161], v[2:3], 1, v[134:135]
	global_store_dwordx4 v[160:161], v[156:159], off
	v_lshl_add_u64 v[138:139], v[138:139], 1, s[70:71]
	s_cbranch_execnz .LBB0_337

; __device__ __forceinline__ unsigned cvt_pk_bf16(float lo, float hi) { f32x2 v = {lo, hi}; bf16x2_t b = __builtin_convertvector(v, bf16x2_t); return __builtin_bit_cast(unsigned, b); }
; __device__ __forceinline__ float bf_lo(unsigned w) { return __uint_as_float(w << 16); }
; __device__ __forceinline__ float bf_hi(unsigned w) { return __uint_as_float(w & 0xffff0000u); }
;     __device__ __forceinline__ void operator()(f32x4 (&acc)[2][2][4][2], const Unit& u, int wr, int wc, int fr, int fq) const {
;     ...
;                 for (int bj = 0; bj < 2; ++bj) { const int c = col0 + bj * HALF;
;                     const u32x4 gb = *(const u32x4*)(Gb + (size_t)r * ldg + c);
;                     float eb[8];
; #pragma unroll
;                     for (int e = 0; e < 4; ++e) { eb[2 * e] = __builtin_amdgcn_exp2f(-1.4426950408889634f * bf_lo(gb[e])); eb[2 * e + 1] = __builtin_amdgcn_exp2f(-1.4426950408889634f * bf_hi(gb[e])); }
;                     if (u.half == 0) { const u32x4 ga = *(const u32x4*)(Ga + (size_t)r * ldg + c);
; #pragma unroll
;                         for (int e = 0; e < 4; ++e) { const float ea0 = __builtin_amdgcn_exp2f(-1.4426950408889634f * bf_lo(ga[e])), ea1 = __builtin_amdgcn_exp2f(-1.4426950408889634f * bf_hi(ga[e]));
;                             acc[ai][bj][m][e >> 1][(2 * e) & 3] *= (1.0f + eb[2 * e]) * __builtin_amdgcn_rcpf(1.0f + ea0);
;                             acc[ai][bj][m][e >> 1][(2 * e + 1) & 3] *= (1.0f + eb[2 * e + 1]) * __builtin_amdgcn_rcpf(1.0f + ea1); } }
;                     else { u32x4 w;
; #pragma unroll
;                         for (int e = 0; e < 4; ++e) { const float a0 = acc[ai][bj][m][e >> 1][(2 * e) & 3] * __builtin_amdgcn_rcpf(1.0f + eb[2 * e]), a1 = acc[ai][bj][m][e >> 1][(2 * e + 1) & 3] * __builtin_amdgcn_rcpf(1.0f + eb[2 * e + 1]);
;                             w[e] = cvt_pk_bf16(a0, a1); }
;                         *(u32x4*)(O + (size_t)r * ldo + c) = w; } } }
.LBB0_337:
	s_and_b64 vcc, exec, s[8:9]
	s_waitcnt vmcnt(14)
	v_mov_b64_e32 v[140:141], v[178:179]
	v_mov_b64_e32 v[142:143], v[180:181]
	v_lshlrev_b32_e32 v0, 16, v140
	v_and_b32_e32 v133, 0xffff0000, v140
	v_lshlrev_b32_e32 v136, 16, v141
	v_and_b32_e32 v137, 0xffff0000, v141
	v_lshlrev_b32_e32 v140, 16, v142
	v_and_b32_e32 v141, 0xffff0000, v142
	v_lshlrev_b32_e32 v142, 16, v143
	v_and_b32_e32 v143, 0xffff0000, v143
	v_mul_f32_e32 v0, 0xbfb8aa3b, v0
	v_mul_f32_e32 v133, 0xbfb8aa3b, v133
	v_mul_f32_e32 v136, 0xbfb8aa3b, v136
	v_mul_f32_e32 v137, 0xbfb8aa3b, v137
	v_mul_f32_e32 v140, 0xbfb8aa3b, v140
	v_mul_f32_e32 v141, 0xbfb8aa3b, v141
	v_mul_f32_e32 v146, 0xbfb8aa3b, v142
	v_mul_f32_e32 v147, 0xbfb8aa3b, v143
	v_exp_f32_e32 v142, v0
	v_exp_f32_e32 v143, v133
	v_exp_f32_e32 v144, v136
	v_exp_f32_e32 v145, v137
	v_exp_f32_e32 v136, v140
	v_exp_f32_e32 v137, v141
	v_exp_f32_e32 v140, v146
	v_exp_f32_e32 v141, v147
	s_cbranch_vccnz .LBB0_378
	v_add_f32_e32 v0, 1.0, v142
	v_rcp_f32_e32 v146, v0
	v_add_f32_e32 v0, 1.0, v143
	v_rcp_f32_e32 v147, v0
	v_add_f32_e32 v0, 1.0, v144
	v_lshl_add_u64 v[134:135], v[2:3], 1, v[134:135]
	v_pk_mul_f32 v[146:147], v[80:81], v[146:147]
	s_nop 0
	v_cvt_pk_bf16_f32 v156, v146, v147
	v_rcp_f32_e32 v146, v0
	v_add_f32_e32 v0, 1.0, v145
	v_rcp_f32_e32 v147, v0
	v_add_f32_e32 v0, 1.0, v136
	v_pk_mul_f32 v[146:147], v[82:83], v[146:147]
	s_nop 0
	v_cvt_pk_bf16_f32 v157, v146, v147
	v_rcp_f32_e32 v146, v0
	v_add_f32_e32 v0, 1.0, v137
	v_rcp_f32_e32 v147, v0
	v_add_f32_e32 v0, 1.0, v140
	v_pk_mul_f32 v[146:147], v[76:77], v[146:147]
	s_nop 0
	v_cvt_pk_bf16_f32 v158, v146, v147
	v_rcp_f32_e32 v146, v0
	v_add_f32_e32 v0, 1.0, v141
	v_rcp_f32_e32 v147, v0
	s_nop 0
	v_pk_mul_f32 v[146:147], v[78:79], v[146:147]
	s_nop 0
	v_cvt_pk_bf16_f32 v159, v146, v147
	global_store_dwordx4 v[134:135], v[156:159], off offset:256
	s_cbranch_execnz .LBB0_340

; __device__ __forceinline__ unsigned cvt_pk_bf16(float lo, float hi) { f32x2 v = {lo, hi}; bf16x2_t b = __builtin_convertvector(v, bf16x2_t); return __builtin_bit_cast(unsigned, b); }
; __device__ __forceinline__ float bf_lo(unsigned w) { return __uint_as_float(w << 16); }
; __device__ __forceinline__ float bf_hi(unsigned w) { return __uint_as_float(w & 0xffff0000u); }
;     __device__ __forceinline__ void operator()(f32x4 (&acc)[2][2][4][2], const Unit& u, int wr, int wc, int fr, int fq) const {
;     ...
;                 for (int bj = 0; bj < 2; ++bj) { const int c = col0 + bj * HALF;
;                     const u32x4 gb = *(const u32x4*)(Gb + (size_t)r * ldg + c);
;                     float eb[8];
; #pragma unroll
;                     for (int e = 0; e < 4; ++e) { eb[2 * e] = __builtin_amdgcn_exp2f(-1.4426950408889634f * bf_lo(gb[e])); eb[2 * e + 1] = __builtin_amdgcn_exp2f(-1.4426950408889634f * bf_hi(gb[e])); }
;                     if (u.half == 0) { const u32x4 ga = *(const u32x4*)(Ga + (size_t)r * ldg + c);
; #pragma unroll
;                         for (int e = 0; e < 4; ++e) { const float ea0 = __builtin_amdgcn_exp2f(-1.4426950408889634f * bf_lo(ga[e])), ea1 = __builtin_amdgcn_exp2f(-1.4426950408889634f * bf_hi(ga[e]));
;                             acc[ai][bj][m][e >> 1][(2 * e) & 3] *= (1.0f + eb[2 * e]) * __builtin_amdgcn_rcpf(1.0f + ea0);
;                             acc[ai][bj][m][e >> 1][(2 * e + 1) & 3] *= (1.0f + eb[2 * e + 1]) * __builtin_amdgcn_rcpf(1.0f + ea1); } }
;                     else { u32x4 w;
; #pragma unroll
;                         for (int e = 0; e < 4; ++e) { const float a0 = acc[ai][bj][m][e >> 1][(2 * e) & 3] * __builtin_amdgcn_rcpf(1.0f + eb[2 * e]), a1 = acc[ai][bj][m][e >> 1][(2 * e + 1) & 3] * __builtin_amdgcn_rcpf(1.0f + eb[2 * e + 1]);
;                             w[e] = cvt_pk_bf16(a0, a1); }
;                         *(u32x4*)(O + (size_t)r * ldo + c) = w; } } }
.LBB0_340:
	v_or_b32_e32 v134, 48, v132
	v_mad_i64_i32 v[138:139], s[26:27], v134, s90, 0
	v_lshl_add_u64 v[136:137], v[138:139], 1, s[72:73]
	v_lshl_add_u64 v[136:137], v[2:3], 1, v[136:137]
	v_ashrrev_i32_e32 v135, 31, v134
	v_lshlrev_b64 v[134:135], 11, v[134:135]
	s_and_b64 vcc, exec, s[8:9]
	v_lshl_add_u64 v[134:135], s[74:75], 0, v[134:135]
	s_waitcnt vmcnt(14)
	v_mov_b64_e32 v[140:141], v[182:183]
	v_mov_b64_e32 v[142:143], v[184:185]
	v_lshlrev_b32_e32 v0, 16, v140
	v_and_b32_e32 v133, 0xffff0000, v140
	v_lshlrev_b32_e32 v140, 16, v141
	v_and_b32_e32 v141, 0xffff0000, v141
	v_lshlrev_b32_e32 v144, 16, v142
	v_and_b32_e32 v142, 0xffff0000, v142
	v_lshlrev_b32_e32 v145, 16, v143
	v_and_b32_e32 v143, 0xffff0000, v143
	v_mul_f32_e32 v0, 0xbfb8aa3b, v0
	v_mul_f32_e32 v133, 0xbfb8aa3b, v133
	v_mul_f32_e32 v140, 0xbfb8aa3b, v140
	v_mul_f32_e32 v141, 0xbfb8aa3b, v141
	v_mul_f32_e32 v156, 0xbfb8aa3b, v144
	v_mul_f32_e32 v142, 0xbfb8aa3b, v142
	v_mul_f32_e32 v157, 0xbfb8aa3b, v145
	v_mul_f32_e32 v143, 0xbfb8aa3b, v143
	v_exp_f32_e32 v144, v0
	v_exp_f32_e32 v145, v133
	v_exp_f32_e32 v146, v140
	v_exp_f32_e32 v147, v141
	v_exp_f32_e32 v140, v156
	v_exp_f32_e32 v141, v142
	v_exp_f32_e32 v142, v157
	v_exp_f32_e32 v143, v143
	s_cbranch_vccnz .LBB0_379
	v_add_f32_e32 v0, 1.0, v144
	v_rcp_f32_e32 v156, v0
	v_add_f32_e32 v0, 1.0, v145
	v_rcp_f32_e32 v157, v0
	v_add_f32_e32 v0, 1.0, v146
	v_rcp_f32_e32 v158, v0
	v_add_f32_e32 v0, 1.0, v147
	v_rcp_f32_e32 v159, v0
	v_pk_mul_f32 v[156:157], v[104:105], v[156:157]
	v_add_f32_e32 v0, 1.0, v140
	v_cvt_pk_bf16_f32 v156, v156, v157
	v_pk_mul_f32 v[158:159], v[106:107], v[158:159]
	s_nop 0
	v_cvt_pk_bf16_f32 v157, v158, v159
	v_rcp_f32_e32 v158, v0
	v_add_f32_e32 v0, 1.0, v141
	v_rcp_f32_e32 v159, v0
	v_add_f32_e32 v0, 1.0, v142
	v_rcp_f32_e32 v160, v0
	v_add_f32_e32 v0, 1.0, v143
	v_rcp_f32_e32 v161, v0
	v_pk_mul_f32 v[158:159], v[100:101], v[158:159]
	v_pk_mul_f32 v[160:161], v[102:103], v[160:161]
	v_cvt_pk_bf16_f32 v158, v158, v159
	v_cvt_pk_bf16_f32 v159, v160, v161
	v_lshl_add_u64 v[160:161], v[2:3], 1, v[134:135]
	global_store_dwordx4 v[160:161], v[156:159], off
	v_lshl_add_u64 v[138:139], v[138:139], 1, s[70:71]
	s_cbranch_execnz .LBB0_343

; __device__ __forceinline__ unsigned cvt_pk_bf16(float lo, float hi) { f32x2 v = {lo, hi}; bf16x2_t b = __builtin_convertvector(v, bf16x2_t); return __builtin_bit_cast(unsigned, b); }
; __device__ __forceinline__ float bf_lo(unsigned w) { return __uint_as_float(w << 16); }
; __device__ __forceinline__ float bf_hi(unsigned w) { return __uint_as_float(w & 0xffff0000u); }
;     __device__ __forceinline__ void operator()(f32x4 (&acc)[2][2][4][2], const Unit& u, int wr, int wc, int fr, int fq) const {
;     ...
;                 for (int bj = 0; bj < 2; ++bj) { const int c = col0 + bj * HALF;
;                     const u32x4 gb = *(const u32x4*)(Gb + (size_t)r * ldg + c);
;                     float eb[8];
; #pragma unroll
;                     for (int e = 0; e < 4; ++e) { eb[2 * e] = __builtin_amdgcn_exp2f(-1.4426950408889634f * bf_lo(gb[e])); eb[2 * e + 1] = __builtin_amdgcn_exp2f(-1.4426950408889634f * bf_hi(gb[e])); }
;                     if (u.half == 0) { const u32x4 ga = *(const u32x4*)(Ga + (size_t)r * ldg + c);
; #pragma unroll
;                         for (int e = 0; e < 4; ++e) { const float ea0 = __builtin_amdgcn_exp2f(-1.4426950408889634f * bf_lo(ga[e])), ea1 = __builtin_amdgcn_exp2f(-1.4426950408889634f * bf_hi(ga[e]));
;                             acc[ai][bj][m][e >> 1][(2 * e) & 3] *= (1.0f + eb[2 * e]) * __builtin_amdgcn_rcpf(1.0f + ea0);
;                             acc[ai][bj][m][e >> 1][(2 * e + 1) & 3] *= (1.0f + eb[2 * e + 1]) * __builtin_amdgcn_rcpf(1.0f + ea1); } }
;                     else { u32x4 w;
; #pragma unroll
;                         for (int e = 0; e < 4; ++e) { const float a0 = acc[ai][bj][m][e >> 1][(2 * e) & 3] * __builtin_amdgcn_rcpf(1.0f + eb[2 * e]), a1 = acc[ai][bj][m][e >> 1][(2 * e + 1) & 3] * __builtin_amdgcn_rcpf(1.0f + eb[2 * e + 1]);
;                             w[e] = cvt_pk_bf16(a0, a1); }
;                         *(u32x4*)(O + (size_t)r * ldo + c) = w; } } }
.LBB0_343:
	s_and_b64 vcc, exec, s[8:9]
	s_waitcnt vmcnt(14)
	v_mov_b64_e32 v[140:141], v[186:187]
	v_mov_b64_e32 v[142:143], v[188:189]
	v_lshlrev_b32_e32 v0, 16, v140
	v_and_b32_e32 v133, 0xffff0000, v140
	v_lshlrev_b32_e32 v136, 16, v141
	v_and_b32_e32 v137, 0xffff0000, v141
	v_lshlrev_b32_e32 v140, 16, v142
	v_and_b32_e32 v141, 0xffff0000, v142
	v_lshlrev_b32_e32 v142, 16, v143
	v_and_b32_e32 v143, 0xffff0000, v143
	v_mul_f32_e32 v0, 0xbfb8aa3b, v0
	v_mul_f32_e32 v133, 0xbfb8aa3b, v133
	v_mul_f32_e32 v136, 0xbfb8aa3b, v136
	v_mul_f32_e32 v137, 0xbfb8aa3b, v137
	v_mul_f32_e32 v140, 0xbfb8aa3b, v140
	v_mul_f32_e32 v141, 0xbfb8aa3b, v141
	v_mul_f32_e32 v146, 0xbfb8aa3b, v142
	v_mul_f32_e32 v147, 0xbfb8aa3b, v143
	v_exp_f32_e32 v142, v0
	v_exp_f32_e32 v143, v133
	v_exp_f32_e32 v144, v136
	v_exp_f32_e32 v145, v137
	v_exp_f32_e32 v136, v140
	v_exp_f32_e32 v137, v141
	v_exp_f32_e32 v140, v146
	v_exp_f32_e32 v141, v147
	s_cbranch_vccnz .LBB0_380
	v_add_f32_e32 v0, 1.0, v142
	v_rcp_f32_e32 v146, v0
	v_add_f32_e32 v0, 1.0, v143
	v_rcp_f32_e32 v147, v0
	v_add_f32_e32 v0, 1.0, v144
	v_lshl_add_u64 v[134:135], v[2:3], 1, v[134:135]
	v_pk_mul_f32 v[146:147], v[72:73], v[146:147]
	s_nop 0
	v_cvt_pk_bf16_f32 v156, v146, v147
	v_rcp_f32_e32 v146, v0
	v_add_f32_e32 v0, 1.0, v145
	v_rcp_f32_e32 v147, v0
	v_add_f32_e32 v0, 1.0, v136
	v_pk_mul_f32 v[146:147], v[74:75], v[146:147]
	s_nop 0
	v_cvt_pk_bf16_f32 v157, v146, v147
	v_rcp_f32_e32 v146, v0
	v_add_f32_e32 v0, 1.0, v137
	v_rcp_f32_e32 v147, v0
	v_add_f32_e32 v0, 1.0, v140
	v_pk_mul_f32 v[146:147], v[68:69], v[146:147]
	s_nop 0
	v_cvt_pk_bf16_f32 v158, v146, v147
	v_rcp_f32_e32 v146, v0
	v_add_f32_e32 v0, 1.0, v141
	v_rcp_f32_e32 v147, v0
	s_nop 0
	v_pk_mul_f32 v[146:147], v[70:71], v[146:147]
	s_nop 0
	v_cvt_pk_bf16_f32 v159, v146, v147
	global_store_dwordx4 v[134:135], v[156:159], off offset:256
	s_cbranch_execnz .LBB0_346

; __device__ __forceinline__ unsigned cvt_pk_bf16(float lo, float hi) { f32x2 v = {lo, hi}; bf16x2_t b = __builtin_convertvector(v, bf16x2_t); return __builtin_bit_cast(unsigned, b); }
; __device__ __forceinline__ float bf_lo(unsigned w) { return __uint_as_float(w << 16); }
; __device__ __forceinline__ float bf_hi(unsigned w) { return __uint_as_float(w & 0xffff0000u); }
;     __device__ __forceinline__ void operator()(f32x4 (&acc)[2][2][4][2], const Unit& u, int wr, int wc, int fr, int fq) const {
;     ...
;                 for (int bj = 0; bj < 2; ++bj) { const int c = col0 + bj * HALF;
;                     const u32x4 gb = *(const u32x4*)(Gb + (size_t)r * ldg + c);
;                     float eb[8];
; #pragma unroll
;                     for (int e = 0; e < 4; ++e) { eb[2 * e] = __builtin_amdgcn_exp2f(-1.4426950408889634f * bf_lo(gb[e])); eb[2 * e + 1] = __builtin_amdgcn_exp2f(-1.4426950408889634f * bf_hi(gb[e])); }
;                     if (u.half == 0) { const u32x4 ga = *(const u32x4*)(Ga + (size_t)r * ldg + c);
; #pragma unroll
;                         for (int e = 0; e < 4; ++e) { const float ea0 = __builtin_amdgcn_exp2f(-1.4426950408889634f * bf_lo(ga[e])), ea1 = __builtin_amdgcn_exp2f(-1.4426950408889634f * bf_hi(ga[e]));
;                             acc[ai][bj][m][e >> 1][(2 * e) & 3] *= (1.0f + eb[2 * e]) * __builtin_amdgcn_rcpf(1.0f + ea0);
;                             acc[ai][bj][m][e >> 1][(2 * e + 1) & 3] *= (1.0f + eb[2 * e + 1]) * __builtin_amdgcn_rcpf(1.0f + ea1); } }
;                     else { u32x4 w;
; #pragma unroll
;                         for (int e = 0; e < 4; ++e) { const float a0 = acc[ai][bj][m][e >> 1][(2 * e) & 3] * __builtin_amdgcn_rcpf(1.0f + eb[2 * e]), a1 = acc[ai][bj][m][e >> 1][(2 * e + 1) & 3] * __builtin_amdgcn_rcpf(1.0f + eb[2 * e + 1]);
;                             w[e] = cvt_pk_bf16(a0, a1); }
;                         *(u32x4*)(O + (size_t)r * ldo + c) = w; } } }
.LBB0_346:
	v_add_u32_e32 v134, 0x80, v132
	v_mad_i64_i32 v[138:139], s[26:27], v134, s90, 0
	v_lshl_add_u64 v[136:137], v[138:139], 1, s[72:73]
	v_lshl_add_u64 v[136:137], v[2:3], 1, v[136:137]
	v_ashrrev_i32_e32 v135, 31, v134
	v_lshlrev_b64 v[134:135], 11, v[134:135]
	s_and_b64 vcc, exec, s[8:9]
	v_lshl_add_u64 v[134:135], s[74:75], 0, v[134:135]
	s_waitcnt vmcnt(14)
	v_mov_b64_e32 v[140:141], v[190:191]
	v_mov_b64_e32 v[142:143], v[192:193]
	v_lshlrev_b32_e32 v0, 16, v140
	v_and_b32_e32 v133, 0xffff0000, v140
	v_lshlrev_b32_e32 v140, 16, v141
	v_and_b32_e32 v141, 0xffff0000, v141
	v_lshlrev_b32_e32 v144, 16, v142
	v_and_b32_e32 v142, 0xffff0000, v142
	v_lshlrev_b32_e32 v145, 16, v143
	v_and_b32_e32 v143, 0xffff0000, v143
	v_mul_f32_e32 v0, 0xbfb8aa3b, v0
	v_mul_f32_e32 v133, 0xbfb8aa3b, v133
	v_mul_f32_e32 v140, 0xbfb8aa3b, v140
	v_mul_f32_e32 v141, 0xbfb8aa3b, v141
	v_mul_f32_e32 v156, 0xbfb8aa3b, v144
	v_mul_f32_e32 v142, 0xbfb8aa3b, v142
	v_mul_f32_e32 v157, 0xbfb8aa3b, v145
	v_mul_f32_e32 v143, 0xbfb8aa3b, v143
	v_exp_f32_e32 v144, v0
	v_exp_f32_e32 v145, v133
	v_exp_f32_e32 v146, v140
	v_exp_f32_e32 v147, v141
	v_exp_f32_e32 v140, v156
	v_exp_f32_e32 v141, v142
	v_exp_f32_e32 v142, v157
	v_exp_f32_e32 v143, v143
	s_cbranch_vccnz .LBB0_381
	v_add_f32_e32 v0, 1.0, v144
	v_rcp_f32_e32 v156, v0
	v_add_f32_e32 v0, 1.0, v145
	v_rcp_f32_e32 v157, v0
	v_add_f32_e32 v0, 1.0, v146
	v_rcp_f32_e32 v158, v0
	v_add_f32_e32 v0, 1.0, v147
	v_rcp_f32_e32 v159, v0
	v_pk_mul_f32 v[156:157], v[64:65], v[156:157]
	v_add_f32_e32 v0, 1.0, v140
	v_cvt_pk_bf16_f32 v156, v156, v157
	v_pk_mul_f32 v[158:159], v[66:67], v[158:159]
	s_nop 0
	v_cvt_pk_bf16_f32 v157, v158, v159
	v_rcp_f32_e32 v158, v0
	v_add_f32_e32 v0, 1.0, v141
	v_rcp_f32_e32 v159, v0
	v_add_f32_e32 v0, 1.0, v142
	v_rcp_f32_e32 v160, v0
	v_add_f32_e32 v0, 1.0, v143
	v_rcp_f32_e32 v161, v0
	v_pk_mul_f32 v[158:159], v[60:61], v[158:159]
	v_pk_mul_f32 v[160:161], v[62:63], v[160:161]
	v_cvt_pk_bf16_f32 v158, v158, v159
	v_cvt_pk_bf16_f32 v159, v160, v161
	v_lshl_add_u64 v[160:161], v[2:3], 1, v[134:135]
	global_store_dwordx4 v[160:161], v[156:159], off
	v_lshl_add_u64 v[138:139], v[138:139], 1, s[70:71]
	s_cbranch_execnz .LBB0_349

; __device__ __forceinline__ unsigned cvt_pk_bf16(float lo, float hi) { f32x2 v = {lo, hi}; bf16x2_t b = __builtin_convertvector(v, bf16x2_t); return __builtin_bit_cast(unsigned, b); }
; __device__ __forceinline__ float bf_lo(unsigned w) { return __uint_as_float(w << 16); }
; __device__ __forceinline__ float bf_hi(unsigned w) { return __uint_as_float(w & 0xffff0000u); }
;     __device__ __forceinline__ void operator()(f32x4 (&acc)[2][2][4][2], const Unit& u, int wr, int wc, int fr, int fq) const {
;     ...
;                 for (int bj = 0; bj < 2; ++bj) { const int c = col0 + bj * HALF;
;                     const u32x4 gb = *(const u32x4*)(Gb + (size_t)r * ldg + c);
;                     float eb[8];
; #pragma unroll
;                     for (int e = 0; e < 4; ++e) { eb[2 * e] = __builtin_amdgcn_exp2f(-1.4426950408889634f * bf_lo(gb[e])); eb[2 * e + 1] = __builtin_amdgcn_exp2f(-1.4426950408889634f * bf_hi(gb[e])); }
;                     if (u.half == 0) { const u32x4 ga = *(const u32x4*)(Ga + (size_t)r * ldg + c);
; #pragma unroll
;                         for (int e = 0; e < 4; ++e) { const float ea0 = __builtin_amdgcn_exp2f(-1.4426950408889634f * bf_lo(ga[e])), ea1 = __builtin_amdgcn_exp2f(-1.4426950408889634f * bf_hi(ga[e]));
;                             acc[ai][bj][m][e >> 1][(2 * e) & 3] *= (1.0f + eb[2 * e]) * __builtin_amdgcn_rcpf(1.0f + ea0);
;                             acc[ai][bj][m][e >> 1][(2 * e + 1) & 3] *= (1.0f + eb[2 * e + 1]) * __builtin_amdgcn_rcpf(1.0f + ea1); } }
;                     else { u32x4 w;
; #pragma unroll
;                         for (int e = 0; e < 4; ++e) { const float a0 = acc[ai][bj][m][e >> 1][(2 * e) & 3] * __builtin_amdgcn_rcpf(1.0f + eb[2 * e]), a1 = acc[ai][bj][m][e >> 1][(2 * e + 1) & 3] * __builtin_amdgcn_rcpf(1.0f + eb[2 * e + 1]);
;                             w[e] = cvt_pk_bf16(a0, a1); }
;                         *(u32x4*)(O + (size_t)r * ldo + c) = w; } } }
.LBB0_349:
	s_and_b64 vcc, exec, s[8:9]
	s_waitcnt vmcnt(14)
	v_mov_b64_e32 v[140:141], v[210:211]
	v_mov_b64_e32 v[142:143], v[212:213]
	v_lshlrev_b32_e32 v0, 16, v140
	v_and_b32_e32 v133, 0xffff0000, v140
	v_lshlrev_b32_e32 v136, 16, v141
	v_and_b32_e32 v137, 0xffff0000, v141
	v_lshlrev_b32_e32 v140, 16, v142
	v_and_b32_e32 v141, 0xffff0000, v142
	v_lshlrev_b32_e32 v142, 16, v143
	v_and_b32_e32 v143, 0xffff0000, v143
	v_mul_f32_e32 v0, 0xbfb8aa3b, v0
	v_mul_f32_e32 v133, 0xbfb8aa3b, v133
	v_mul_f32_e32 v136, 0xbfb8aa3b, v136
	v_mul_f32_e32 v137, 0xbfb8aa3b, v137
	v_mul_f32_e32 v140, 0xbfb8aa3b, v140
	v_mul_f32_e32 v141, 0xbfb8aa3b, v141
	v_mul_f32_e32 v146, 0xbfb8aa3b, v142
	v_mul_f32_e32 v147, 0xbfb8aa3b, v143
	v_exp_f32_e32 v142, v0
	v_exp_f32_e32 v143, v133
	v_exp_f32_e32 v144, v136
	v_exp_f32_e32 v145, v137
	v_exp_f32_e32 v136, v140
	v_exp_f32_e32 v137, v141
	v_exp_f32_e32 v140, v146
	v_exp_f32_e32 v141, v147
	s_cbranch_vccnz .LBB0_382
	v_add_f32_e32 v0, 1.0, v142
	v_rcp_f32_e32 v146, v0
	v_add_f32_e32 v0, 1.0, v143
	v_rcp_f32_e32 v147, v0
	v_add_f32_e32 v0, 1.0, v144
	v_lshl_add_u64 v[134:135], v[2:3], 1, v[134:135]
	v_pk_mul_f32 v[146:147], v[32:33], v[146:147]
	s_nop 0
	v_cvt_pk_bf16_f32 v156, v146, v147
	v_rcp_f32_e32 v146, v0
	v_add_f32_e32 v0, 1.0, v145
	v_rcp_f32_e32 v147, v0
	v_add_f32_e32 v0, 1.0, v136
	v_pk_mul_f32 v[146:147], v[34:35], v[146:147]
	s_nop 0
	v_cvt_pk_bf16_f32 v157, v146, v147
	v_rcp_f32_e32 v146, v0
	v_add_f32_e32 v0, 1.0, v137
	v_rcp_f32_e32 v147, v0
	v_add_f32_e32 v0, 1.0, v140
	v_pk_mul_f32 v[146:147], v[28:29], v[146:147]
	s_nop 0
	v_cvt_pk_bf16_f32 v158, v146, v147
	v_rcp_f32_e32 v146, v0
	v_add_f32_e32 v0, 1.0, v141
	v_rcp_f32_e32 v147, v0
	s_nop 0
	v_pk_mul_f32 v[146:147], v[30:31], v[146:147]
	s_nop 0
	v_cvt_pk_bf16_f32 v159, v146, v147
	global_store_dwordx4 v[134:135], v[156:159], off offset:256
	s_cbranch_execnz .LBB0_352

; __device__ __forceinline__ unsigned cvt_pk_bf16(float lo, float hi) { f32x2 v = {lo, hi}; bf16x2_t b = __builtin_convertvector(v, bf16x2_t); return __builtin_bit_cast(unsigned, b); }
; __device__ __forceinline__ float bf_lo(unsigned w) { return __uint_as_float(w << 16); }
; __device__ __forceinline__ float bf_hi(unsigned w) { return __uint_as_float(w & 0xffff0000u); }
;     __device__ __forceinline__ void operator()(f32x4 (&acc)[2][2][4][2], const Unit& u, int wr, int wc, int fr, int fq) const {
;     ...
;                 for (int bj = 0; bj < 2; ++bj) { const int c = col0 + bj * HALF;
;                     const u32x4 gb = *(const u32x4*)(Gb + (size_t)r * ldg + c);
;                     float eb[8];
; #pragma unroll
;                     for (int e = 0; e < 4; ++e) { eb[2 * e] = __builtin_amdgcn_exp2f(-1.4426950408889634f * bf_lo(gb[e])); eb[2 * e + 1] = __builtin_amdgcn_exp2f(-1.4426950408889634f * bf_hi(gb[e])); }
;                     if (u.half == 0) { const u32x4 ga = *(const u32x4*)(Ga + (size_t)r * ldg + c);
; #pragma unroll
;                         for (int e = 0; e < 4; ++e) { const float ea0 = __builtin_amdgcn_exp2f(-1.4426950408889634f * bf_lo(ga[e])), ea1 = __builtin_amdgcn_exp2f(-1.4426950408889634f * bf_hi(ga[e]));
;                             acc[ai][bj][m][e >> 1][(2 * e) & 3] *= (1.0f + eb[2 * e]) * __builtin_amdgcn_rcpf(1.0f + ea0);
;                             acc[ai][bj][m][e >> 1][(2 * e + 1) & 3] *= (1.0f + eb[2 * e + 1]) * __builtin_amdgcn_rcpf(1.0f + ea1); } }
;                     else { u32x4 w;
; #pragma unroll
;                         for (int e = 0; e < 4; ++e) { const float a0 = acc[ai][bj][m][e >> 1][(2 * e) & 3] * __builtin_amdgcn_rcpf(1.0f + eb[2 * e]), a1 = acc[ai][bj][m][e >> 1][(2 * e + 1) & 3] * __builtin_amdgcn_rcpf(1.0f + eb[2 * e + 1]);
;                             w[e] = cvt_pk_bf16(a0, a1); }
;                         *(u32x4*)(O + (size_t)r * ldo + c) = w; } } }
.LBB0_352:
	v_add_u32_e32 v134, 0x90, v132
	v_mad_i64_i32 v[138:139], s[26:27], v134, s90, 0
	v_lshl_add_u64 v[136:137], v[138:139], 1, s[72:73]
	v_lshl_add_u64 v[136:137], v[2:3], 1, v[136:137]
	v_ashrrev_i32_e32 v135, 31, v134
	v_lshlrev_b64 v[134:135], 11, v[134:135]
	s_and_b64 vcc, exec, s[8:9]
	v_lshl_add_u64 v[134:135], s[74:75], 0, v[134:135]
	s_waitcnt vmcnt(14)
	v_mov_b64_e32 v[140:141], v[214:215]
	v_mov_b64_e32 v[142:143], v[216:217]
	v_lshlrev_b32_e32 v0, 16, v140
	v_and_b32_e32 v133, 0xffff0000, v140
	v_lshlrev_b32_e32 v140, 16, v141
	v_and_b32_e32 v141, 0xffff0000, v141
	v_lshlrev_b32_e32 v144, 16, v142
	v_and_b32_e32 v142, 0xffff0000, v142
	v_lshlrev_b32_e32 v145, 16, v143
	v_and_b32_e32 v143, 0xffff0000, v143
	v_mul_f32_e32 v0, 0xbfb8aa3b, v0
	v_mul_f32_e32 v133, 0xbfb8aa3b, v133
	v_mul_f32_e32 v140, 0xbfb8aa3b, v140
	v_mul_f32_e32 v141, 0xbfb8aa3b, v141
	v_mul_f32_e32 v156, 0xbfb8aa3b, v144
	v_mul_f32_e32 v142, 0xbfb8aa3b, v142
	v_mul_f32_e32 v157, 0xbfb8aa3b, v145
	v_mul_f32_e32 v143, 0xbfb8aa3b, v143
	v_exp_f32_e32 v144, v0
	v_exp_f32_e32 v145, v133
	v_exp_f32_e32 v146, v140
	v_exp_f32_e32 v147, v141
	v_exp_f32_e32 v140, v156
	v_exp_f32_e32 v141, v142
	v_exp_f32_e32 v142, v157
	v_exp_f32_e32 v143, v143
	s_cbranch_vccnz .LBB0_383
	v_add_f32_e32 v0, 1.0, v144
	v_rcp_f32_e32 v156, v0
	v_add_f32_e32 v0, 1.0, v145
	v_rcp_f32_e32 v157, v0
	v_add_f32_e32 v0, 1.0, v146
	v_rcp_f32_e32 v158, v0
	v_add_f32_e32 v0, 1.0, v147
	v_rcp_f32_e32 v159, v0
	v_pk_mul_f32 v[156:157], v[56:57], v[156:157]
	v_add_f32_e32 v0, 1.0, v140
	v_cvt_pk_bf16_f32 v156, v156, v157
	v_pk_mul_f32 v[158:159], v[58:59], v[158:159]
	s_nop 0
	v_cvt_pk_bf16_f32 v157, v158, v159
	v_rcp_f32_e32 v158, v0
	v_add_f32_e32 v0, 1.0, v141
	v_rcp_f32_e32 v159, v0
	v_add_f32_e32 v0, 1.0, v142
	v_rcp_f32_e32 v160, v0
	v_add_f32_e32 v0, 1.0, v143
	v_rcp_f32_e32 v161, v0
	v_pk_mul_f32 v[158:159], v[52:53], v[158:159]
	v_pk_mul_f32 v[160:161], v[54:55], v[160:161]
	v_cvt_pk_bf16_f32 v158, v158, v159
	v_cvt_pk_bf16_f32 v159, v160, v161
	v_lshl_add_u64 v[160:161], v[2:3], 1, v[134:135]
	global_store_dwordx4 v[160:161], v[156:159], off
	v_lshl_add_u64 v[138:139], v[138:139], 1, s[70:71]
	s_cbranch_execnz .LBB0_355

; __device__ __forceinline__ unsigned cvt_pk_bf16(float lo, float hi) { f32x2 v = {lo, hi}; bf16x2_t b = __builtin_convertvector(v, bf16x2_t); return __builtin_bit_cast(unsigned, b); }
; __device__ __forceinline__ float bf_lo(unsigned w) { return __uint_as_float(w << 16); }
; __device__ __forceinline__ float bf_hi(unsigned w) { return __uint_as_float(w & 0xffff0000u); }
;     __device__ __forceinline__ void operator()(f32x4 (&acc)[2][2][4][2], const Unit& u, int wr, int wc, int fr, int fq) const {
;     ...
;                 for (int bj = 0; bj < 2; ++bj) { const int c = col0 + bj * HALF;
;                     const u32x4 gb = *(const u32x4*)(Gb + (size_t)r * ldg + c);
;                     float eb[8];
; #pragma unroll
;                     for (int e = 0; e < 4; ++e) { eb[2 * e] = __builtin_amdgcn_exp2f(-1.4426950408889634f * bf_lo(gb[e])); eb[2 * e + 1] = __builtin_amdgcn_exp2f(-1.4426950408889634f * bf_hi(gb[e])); }
;                     if (u.half == 0) { const u32x4 ga = *(const u32x4*)(Ga + (size_t)r * ldg + c);
; #pragma unroll
;                         for (int e = 0; e < 4; ++e) { const float ea0 = __builtin_amdgcn_exp2f(-1.4426950408889634f * bf_lo(ga[e])), ea1 = __builtin_amdgcn_exp2f(-1.4426950408889634f * bf_hi(ga[e]));
;                             acc[ai][bj][m][e >> 1][(2 * e) & 3] *= (1.0f + eb[2 * e]) * __builtin_amdgcn_rcpf(1.0f + ea0);
;                             acc[ai][bj][m][e >> 1][(2 * e + 1) & 3] *= (1.0f + eb[2 * e + 1]) * __builtin_amdgcn_rcpf(1.0f + ea1); } }
;                     else { u32x4 w;
; #pragma unroll
;                         for (int e = 0; e < 4; ++e) { const float a0 = acc[ai][bj][m][e >> 1][(2 * e) & 3] * __builtin_amdgcn_rcpf(1.0f + eb[2 * e]), a1 = acc[ai][bj][m][e >> 1][(2 * e + 1) & 3] * __builtin_amdgcn_rcpf(1.0f + eb[2 * e + 1]);
;                             w[e] = cvt_pk_bf16(a0, a1); }
;                         *(u32x4*)(O + (size_t)r * ldo + c) = w; } } }
.LBB0_355:
	s_and_b64 vcc, exec, s[8:9]
	s_waitcnt vmcnt(14)
	v_mov_b64_e32 v[140:141], v[218:219]
	v_mov_b64_e32 v[142:143], v[220:221]
	v_lshlrev_b32_e32 v0, 16, v140
	v_and_b32_e32 v133, 0xffff0000, v140
	v_lshlrev_b32_e32 v136, 16, v141
	v_and_b32_e32 v137, 0xffff0000, v141
	v_lshlrev_b32_e32 v140, 16, v142
	v_and_b32_e32 v141, 0xffff0000, v142
	v_lshlrev_b32_e32 v142, 16, v143
	v_and_b32_e32 v143, 0xffff0000, v143
	v_mul_f32_e32 v0, 0xbfb8aa3b, v0
	v_mul_f32_e32 v133, 0xbfb8aa3b, v133
	v_mul_f32_e32 v136, 0xbfb8aa3b, v136
	v_mul_f32_e32 v137, 0xbfb8aa3b, v137
	v_mul_f32_e32 v140, 0xbfb8aa3b, v140
	v_mul_f32_e32 v141, 0xbfb8aa3b, v141
	v_mul_f32_e32 v146, 0xbfb8aa3b, v142
	v_mul_f32_e32 v147, 0xbfb8aa3b, v143
	v_exp_f32_e32 v142, v0
	v_exp_f32_e32 v143, v133
	v_exp_f32_e32 v144, v136
	v_exp_f32_e32 v145, v137
	v_exp_f32_e32 v136, v140
	v_exp_f32_e32 v137, v141
	v_exp_f32_e32 v140, v146
	v_exp_f32_e32 v141, v147
	s_cbranch_vccnz .LBB0_384
	v_add_f32_e32 v0, 1.0, v142
	v_rcp_f32_e32 v146, v0
	v_add_f32_e32 v0, 1.0, v143
	v_rcp_f32_e32 v147, v0
	v_add_f32_e32 v0, 1.0, v144
	v_lshl_add_u64 v[134:135], v[2:3], 1, v[134:135]
	v_pk_mul_f32 v[146:147], v[24:25], v[146:147]
	s_nop 0
	v_cvt_pk_bf16_f32 v156, v146, v147
	v_rcp_f32_e32 v146, v0
	v_add_f32_e32 v0, 1.0, v145
	v_rcp_f32_e32 v147, v0
	v_add_f32_e32 v0, 1.0, v136
	v_pk_mul_f32 v[146:147], v[26:27], v[146:147]
	s_nop 0
	v_cvt_pk_bf16_f32 v157, v146, v147
	v_rcp_f32_e32 v146, v0
	v_add_f32_e32 v0, 1.0, v137
	v_rcp_f32_e32 v147, v0
	v_add_f32_e32 v0, 1.0, v140
	v_pk_mul_f32 v[146:147], v[20:21], v[146:147]
	s_nop 0
	v_cvt_pk_bf16_f32 v158, v146, v147
	v_rcp_f32_e32 v146, v0
	v_add_f32_e32 v0, 1.0, v141
	v_rcp_f32_e32 v147, v0
	s_nop 0
	v_pk_mul_f32 v[146:147], v[22:23], v[146:147]
	s_nop 0
	v_cvt_pk_bf16_f32 v159, v146, v147
	global_store_dwordx4 v[134:135], v[156:159], off offset:256
	s_cbranch_execnz .LBB0_358

; __device__ __forceinline__ unsigned cvt_pk_bf16(float lo, float hi) { f32x2 v = {lo, hi}; bf16x2_t b = __builtin_convertvector(v, bf16x2_t); return __builtin_bit_cast(unsigned, b); }
; __device__ __forceinline__ float bf_lo(unsigned w) { return __uint_as_float(w << 16); }
; __device__ __forceinline__ float bf_hi(unsigned w) { return __uint_as_float(w & 0xffff0000u); }
;     __device__ __forceinline__ void operator()(f32x4 (&acc)[2][2][4][2], const Unit& u, int wr, int wc, int fr, int fq) const {
;     ...
;                 for (int bj = 0; bj < 2; ++bj) { const int c = col0 + bj * HALF;
;                     const u32x4 gb = *(const u32x4*)(Gb + (size_t)r * ldg + c);
;                     float eb[8];
; #pragma unroll
;                     for (int e = 0; e < 4; ++e) { eb[2 * e] = __builtin_amdgcn_exp2f(-1.4426950408889634f * bf_lo(gb[e])); eb[2 * e + 1] = __builtin_amdgcn_exp2f(-1.4426950408889634f * bf_hi(gb[e])); }
;                     if (u.half == 0) { const u32x4 ga = *(const u32x4*)(Ga + (size_t)r * ldg + c);
; #pragma unroll
;                         for (int e = 0; e < 4; ++e) { const float ea0 = __builtin_amdgcn_exp2f(-1.4426950408889634f * bf_lo(ga[e])), ea1 = __builtin_amdgcn_exp2f(-1.4426950408889634f * bf_hi(ga[e]));
;                             acc[ai][bj][m][e >> 1][(2 * e) & 3] *= (1.0f + eb[2 * e]) * __builtin_amdgcn_rcpf(1.0f + ea0);
;                             acc[ai][bj][m][e >> 1][(2 * e + 1) & 3] *= (1.0f + eb[2 * e + 1]) * __builtin_amdgcn_rcpf(1.0f + ea1); } }
;                     else { u32x4 w;
; #pragma unroll
;                         for (int e = 0; e < 4; ++e) { const float a0 = acc[ai][bj][m][e >> 1][(2 * e) & 3] * __builtin_amdgcn_rcpf(1.0f + eb[2 * e]), a1 = acc[ai][bj][m][e >> 1][(2 * e + 1) & 3] * __builtin_amdgcn_rcpf(1.0f + eb[2 * e + 1]);
;                             w[e] = cvt_pk_bf16(a0, a1); }
;                         *(u32x4*)(O + (size_t)r * ldo + c) = w; } } }
.LBB0_358:
	v_add_u32_e32 v134, 0xa0, v132
	v_mad_i64_i32 v[138:139], s[26:27], v134, s90, 0
	v_lshl_add_u64 v[136:137], v[138:139], 1, s[72:73]
	v_lshl_add_u64 v[136:137], v[2:3], 1, v[136:137]
	v_ashrrev_i32_e32 v135, 31, v134
	v_lshlrev_b64 v[134:135], 11, v[134:135]
	s_and_b64 vcc, exec, s[8:9]
	v_lshl_add_u64 v[134:135], s[74:75], 0, v[134:135]
	s_waitcnt vmcnt(14)
	v_mov_b64_e32 v[140:141], v[222:223]
	v_mov_b64_e32 v[142:143], v[224:225]
	v_lshlrev_b32_e32 v0, 16, v140
	v_and_b32_e32 v133, 0xffff0000, v140
	v_lshlrev_b32_e32 v140, 16, v141
	v_and_b32_e32 v141, 0xffff0000, v141
	v_lshlrev_b32_e32 v144, 16, v142
	v_and_b32_e32 v142, 0xffff0000, v142
	v_lshlrev_b32_e32 v145, 16, v143
	v_and_b32_e32 v143, 0xffff0000, v143
	v_mul_f32_e32 v0, 0xbfb8aa3b, v0
	v_mul_f32_e32 v133, 0xbfb8aa3b, v133
	v_mul_f32_e32 v140, 0xbfb8aa3b, v140
	v_mul_f32_e32 v141, 0xbfb8aa3b, v141
	v_mul_f32_e32 v156, 0xbfb8aa3b, v144
	v_mul_f32_e32 v142, 0xbfb8aa3b, v142
	v_mul_f32_e32 v157, 0xbfb8aa3b, v145
	v_mul_f32_e32 v143, 0xbfb8aa3b, v143
	v_exp_f32_e32 v144, v0
	v_exp_f32_e32 v145, v133
	v_exp_f32_e32 v146, v140
	v_exp_f32_e32 v147, v141
	v_exp_f32_e32 v140, v156
	v_exp_f32_e32 v141, v142
	v_exp_f32_e32 v142, v157
	v_exp_f32_e32 v143, v143
	s_cbranch_vccnz .LBB0_385
	v_add_f32_e32 v0, 1.0, v144
	v_rcp_f32_e32 v156, v0
	v_add_f32_e32 v0, 1.0, v145
	v_rcp_f32_e32 v157, v0
	v_add_f32_e32 v0, 1.0, v146
	v_rcp_f32_e32 v158, v0
	v_add_f32_e32 v0, 1.0, v147
	v_rcp_f32_e32 v159, v0
	v_pk_mul_f32 v[156:157], v[48:49], v[156:157]
	v_add_f32_e32 v0, 1.0, v140
	v_cvt_pk_bf16_f32 v156, v156, v157
	v_pk_mul_f32 v[158:159], v[50:51], v[158:159]
	s_nop 0
	v_cvt_pk_bf16_f32 v157, v158, v159
	v_rcp_f32_e32 v158, v0
	v_add_f32_e32 v0, 1.0, v141
	v_rcp_f32_e32 v159, v0
	v_add_f32_e32 v0, 1.0, v142
	v_rcp_f32_e32 v160, v0
	v_add_f32_e32 v0, 1.0, v143
	v_rcp_f32_e32 v161, v0
	v_pk_mul_f32 v[158:159], v[44:45], v[158:159]
	v_pk_mul_f32 v[160:161], v[46:47], v[160:161]
	v_cvt_pk_bf16_f32 v158, v158, v159
	v_cvt_pk_bf16_f32 v159, v160, v161
	v_lshl_add_u64 v[160:161], v[2:3], 1, v[134:135]
	global_store_dwordx4 v[160:161], v[156:159], off
	v_lshl_add_u64 v[138:139], v[138:139], 1, s[70:71]
	s_cbranch_execnz .LBB0_361

; __device__ __forceinline__ unsigned cvt_pk_bf16(float lo, float hi) { f32x2 v = {lo, hi}; bf16x2_t b = __builtin_convertvector(v, bf16x2_t); return __builtin_bit_cast(unsigned, b); }
; __device__ __forceinline__ float bf_lo(unsigned w) { return __uint_as_float(w << 16); }
; __device__ __forceinline__ float bf_hi(unsigned w) { return __uint_as_float(w & 0xffff0000u); }
;     __device__ __forceinline__ void operator()(f32x4 (&acc)[2][2][4][2], const Unit& u, int wr, int wc, int fr, int fq) const {
;     ...
;                 for (int bj = 0; bj < 2; ++bj) { const int c = col0 + bj * HALF;
;                     const u32x4 gb = *(const u32x4*)(Gb + (size_t)r * ldg + c);
;                     float eb[8];
; #pragma unroll
;                     for (int e = 0; e < 4; ++e) { eb[2 * e] = __builtin_amdgcn_exp2f(-1.4426950408889634f * bf_lo(gb[e])); eb[2 * e + 1] = __builtin_amdgcn_exp2f(-1.4426950408889634f * bf_hi(gb[e])); }
;                     if (u.half == 0) { const u32x4 ga = *(const u32x4*)(Ga + (size_t)r * ldg + c);
; #pragma unroll
;                         for (int e = 0; e < 4; ++e) { const float ea0 = __builtin_amdgcn_exp2f(-1.4426950408889634f * bf_lo(ga[e])), ea1 = __builtin_amdgcn_exp2f(-1.4426950408889634f * bf_hi(ga[e]));
;                             acc[ai][bj][m][e >> 1][(2 * e) & 3] *= (1.0f + eb[2 * e]) * __builtin_amdgcn_rcpf(1.0f + ea0);
;                             acc[ai][bj][m][e >> 1][(2 * e + 1) & 3] *= (1.0f + eb[2 * e + 1]) * __builtin_amdgcn_rcpf(1.0f + ea1); } }
;                     else { u32x4 w;
; #pragma unroll
;                         for (int e = 0; e < 4; ++e) { const float a0 = acc[ai][bj][m][e >> 1][(2 * e) & 3] * __builtin_amdgcn_rcpf(1.0f + eb[2 * e]), a1 = acc[ai][bj][m][e >> 1][(2 * e + 1) & 3] * __builtin_amdgcn_rcpf(1.0f + eb[2 * e + 1]);
;                             w[e] = cvt_pk_bf16(a0, a1); }
;                         *(u32x4*)(O + (size_t)r * ldo + c) = w; } } }
.LBB0_361:
	s_and_b64 vcc, exec, s[8:9]
	s_waitcnt vmcnt(14)
	v_mov_b64_e32 v[140:141], v[230:231]
	v_mov_b64_e32 v[142:143], v[232:233]
	v_lshlrev_b32_e32 v0, 16, v140
	v_and_b32_e32 v133, 0xffff0000, v140
	v_lshlrev_b32_e32 v136, 16, v141
	v_and_b32_e32 v137, 0xffff0000, v141
	v_lshlrev_b32_e32 v140, 16, v142
	v_and_b32_e32 v141, 0xffff0000, v142
	v_lshlrev_b32_e32 v142, 16, v143
	v_and_b32_e32 v143, 0xffff0000, v143
	v_mul_f32_e32 v0, 0xbfb8aa3b, v0
	v_mul_f32_e32 v133, 0xbfb8aa3b, v133
	v_mul_f32_e32 v136, 0xbfb8aa3b, v136
	v_mul_f32_e32 v137, 0xbfb8aa3b, v137
	v_mul_f32_e32 v140, 0xbfb8aa3b, v140
	v_mul_f32_e32 v141, 0xbfb8aa3b, v141
	v_mul_f32_e32 v146, 0xbfb8aa3b, v142
	v_mul_f32_e32 v147, 0xbfb8aa3b, v143
	v_exp_f32_e32 v142, v0
	v_exp_f32_e32 v143, v133
	v_exp_f32_e32 v144, v136
	v_exp_f32_e32 v145, v137
	v_exp_f32_e32 v136, v140
	v_exp_f32_e32 v137, v141
	v_exp_f32_e32 v140, v146
	v_exp_f32_e32 v141, v147
	s_cbranch_vccnz .LBB0_386
	v_add_f32_e32 v0, 1.0, v142
	v_rcp_f32_e32 v146, v0
	v_add_f32_e32 v0, 1.0, v143
	v_rcp_f32_e32 v147, v0
	v_add_f32_e32 v0, 1.0, v144
	v_lshl_add_u64 v[134:135], v[2:3], 1, v[134:135]
	v_pk_mul_f32 v[146:147], v[16:17], v[146:147]
	s_nop 0
	v_cvt_pk_bf16_f32 v156, v146, v147
	v_rcp_f32_e32 v146, v0
	v_add_f32_e32 v0, 1.0, v145
	v_rcp_f32_e32 v147, v0
	v_add_f32_e32 v0, 1.0, v136
	v_pk_mul_f32 v[146:147], v[18:19], v[146:147]
	s_nop 0
	v_cvt_pk_bf16_f32 v157, v146, v147
	v_rcp_f32_e32 v146, v0
	v_add_f32_e32 v0, 1.0, v137
	v_rcp_f32_e32 v147, v0
	v_add_f32_e32 v0, 1.0, v140
	v_pk_mul_f32 v[146:147], v[12:13], v[146:147]
	s_nop 0
	v_cvt_pk_bf16_f32 v158, v146, v147
	v_rcp_f32_e32 v146, v0
	v_add_f32_e32 v0, 1.0, v141
	v_rcp_f32_e32 v147, v0
	s_nop 0
	v_pk_mul_f32 v[146:147], v[14:15], v[146:147]
	s_nop 0
	v_cvt_pk_bf16_f32 v159, v146, v147
	global_store_dwordx4 v[134:135], v[156:159], off offset:256
	s_cbranch_execnz .LBB0_364

; __device__ __forceinline__ unsigned cvt_pk_bf16(float lo, float hi) { f32x2 v = {lo, hi}; bf16x2_t b = __builtin_convertvector(v, bf16x2_t); return __builtin_bit_cast(unsigned, b); }
; __device__ __forceinline__ float bf_lo(unsigned w) { return __uint_as_float(w << 16); }
; __device__ __forceinline__ float bf_hi(unsigned w) { return __uint_as_float(w & 0xffff0000u); }
;     __device__ __forceinline__ void operator()(f32x4 (&acc)[2][2][4][2], const Unit& u, int wr, int wc, int fr, int fq) const {
;     ...
;                 for (int bj = 0; bj < 2; ++bj) { const int c = col0 + bj * HALF;
;                     const u32x4 gb = *(const u32x4*)(Gb + (size_t)r * ldg + c);
;                     float eb[8];
; #pragma unroll
;                     for (int e = 0; e < 4; ++e) { eb[2 * e] = __builtin_amdgcn_exp2f(-1.4426950408889634f * bf_lo(gb[e])); eb[2 * e + 1] = __builtin_amdgcn_exp2f(-1.4426950408889634f * bf_hi(gb[e])); }
;                     if (u.half == 0) { const u32x4 ga = *(const u32x4*)(Ga + (size_t)r * ldg + c);
; #pragma unroll
;                         for (int e = 0; e < 4; ++e) { const float ea0 = __builtin_amdgcn_exp2f(-1.4426950408889634f * bf_lo(ga[e])), ea1 = __builtin_amdgcn_exp2f(-1.4426950408889634f * bf_hi(ga[e]));
;                             acc[ai][bj][m][e >> 1][(2 * e) & 3] *= (1.0f + eb[2 * e]) * __builtin_amdgcn_rcpf(1.0f + ea0);
;                             acc[ai][bj][m][e >> 1][(2 * e + 1) & 3] *= (1.0f + eb[2 * e + 1]) * __builtin_amdgcn_rcpf(1.0f + ea1); } }
;                     else { u32x4 w;
; #pragma unroll
;                         for (int e = 0; e < 4; ++e) { const float a0 = acc[ai][bj][m][e >> 1][(2 * e) & 3] * __builtin_amdgcn_rcpf(1.0f + eb[2 * e]), a1 = acc[ai][bj][m][e >> 1][(2 * e + 1) & 3] * __builtin_amdgcn_rcpf(1.0f + eb[2 * e + 1]);
;                             w[e] = cvt_pk_bf16(a0, a1); }
;                         *(u32x4*)(O + (size_t)r * ldo + c) = w; } } }
.LBB0_364:
	v_add_u32_e32 v132, 0xb0, v132
	v_mad_i64_i32 v[136:137], s[26:27], v132, s90, 0
	v_lshl_add_u64 v[134:135], v[136:137], 1, s[72:73]
	v_lshl_add_u64 v[134:135], v[2:3], 1, v[134:135]
	v_ashrrev_i32_e32 v133, 31, v132
	v_lshlrev_b64 v[132:133], 11, v[132:133]
	s_and_b64 vcc, exec, s[8:9]
	v_lshl_add_u64 v[132:133], s[74:75], 0, v[132:133]
	s_waitcnt vmcnt(14)
	v_mov_b64_e32 v[138:139], v[234:235]
	v_mov_b64_e32 v[140:141], v[236:237]
	v_lshlrev_b32_e32 v0, 16, v138
	v_and_b32_e32 v138, 0xffff0000, v138
	v_lshlrev_b32_e32 v142, 16, v139
	v_and_b32_e32 v139, 0xffff0000, v139
	v_lshlrev_b32_e32 v143, 16, v140
	v_and_b32_e32 v140, 0xffff0000, v140
	v_lshlrev_b32_e32 v144, 16, v141
	v_and_b32_e32 v141, 0xffff0000, v141
	v_mul_f32_e32 v0, 0xbfb8aa3b, v0
	v_mul_f32_e32 v138, 0xbfb8aa3b, v138
	v_mul_f32_e32 v145, 0xbfb8aa3b, v142
	v_mul_f32_e32 v139, 0xbfb8aa3b, v139
	v_mul_f32_e32 v146, 0xbfb8aa3b, v143
	v_mul_f32_e32 v140, 0xbfb8aa3b, v140
	v_mul_f32_e32 v147, 0xbfb8aa3b, v144
	v_mul_f32_e32 v141, 0xbfb8aa3b, v141
	v_exp_f32_e32 v142, v0
	v_exp_f32_e32 v143, v138
	v_exp_f32_e32 v144, v145
	v_exp_f32_e32 v145, v139
	v_exp_f32_e32 v138, v146
	v_exp_f32_e32 v139, v140
	v_exp_f32_e32 v140, v147
	v_exp_f32_e32 v141, v141
	s_cbranch_vccnz .LBB0_387
	v_add_f32_e32 v0, 1.0, v142
	v_rcp_f32_e32 v146, v0
	v_add_f32_e32 v0, 1.0, v143
	v_rcp_f32_e32 v147, v0
	v_add_f32_e32 v0, 1.0, v144
	v_pk_mul_f32 v[146:147], v[40:41], v[146:147]
	s_nop 0
	v_cvt_pk_bf16_f32 v156, v146, v147
	v_rcp_f32_e32 v146, v0
	v_add_f32_e32 v0, 1.0, v145
	v_rcp_f32_e32 v147, v0
	v_add_f32_e32 v0, 1.0, v138
	v_pk_mul_f32 v[146:147], v[42:43], v[146:147]
	s_nop 0
	v_cvt_pk_bf16_f32 v157, v146, v147
	v_rcp_f32_e32 v146, v0
	v_add_f32_e32 v0, 1.0, v139
	v_rcp_f32_e32 v147, v0
	v_add_f32_e32 v0, 1.0, v140
	v_pk_mul_f32 v[146:147], v[36:37], v[146:147]
	s_nop 0
	v_cvt_pk_bf16_f32 v158, v146, v147
	v_rcp_f32_e32 v146, v0
	v_add_f32_e32 v0, 1.0, v141
	v_rcp_f32_e32 v147, v0
	s_nop 0
	v_pk_mul_f32 v[146:147], v[38:39], v[146:147]
	s_nop 0
	v_cvt_pk_bf16_f32 v159, v146, v147
	v_lshl_add_u64 v[146:147], v[2:3], 1, v[132:133]
	global_store_dwordx4 v[146:147], v[156:159], off
	v_lshl_add_u64 v[136:137], v[136:137], 1, s[70:71]
	s_cbranch_execnz .LBB0_367
